# dense attention item on 32x32x16 bf16 MFMA (one 32-query block per wave): half the MFMA issue slots and cross-lane reductions
# speedup vs baseline: 1.0065x; 1.0009x over previous
; #define LAS __attribute__((address_space(3)))
; DI int otid() { int t = threadIdx.x; asm volatile("" : "+v"(t)); return t; }
; template <int DK>
; DI void dense_attn_item(LAS unsigned char* lds, const bf16_t* Qb, int ldq, const bf16_t* Kb, int ldk, const bf16_t* Kpe, const bf16_t* Vt, int nkeys, float sl2, bf16_t* Ob) {
;     const int tid = otid(), lane = tid & 63, wid = tid >> 6, r16 = lane & 15, q4 = lane >> 4;
;     constexpr int KS = DK / 32, KCH = DK / 8, KROW = DK * 2 + 16, KTILE = 64 * KROW, VROW = 144, VTILE = 128 * VROW, NKL = (64 * KCH) / 512;
;     bf16x8 qf[2][KS];
; #pragma unroll
;     for (int qg = 0; qg < 2; ++qg)
; #pragma unroll
;         for (int ks = 0; ks < KS; ++ks) qf[qg][ks] = *(const bf16x8*)(Qb + (size_t)(wid * 32 + qg * 16 + r16) * ldq + ks * 32 + q4 * 8);
;     f32x4 oacc[2][8];
; #pragma unroll
;     for (int qg = 0; qg < 2; ++qg)
; #pragma unroll
;         for (int d = 0; d < 8; ++d) oacc[qg][d] = (f32x4){0.f, 0.f, 0.f, 0.f};
;     float mrun[2] = {-1e30f, -1e30f}, lsum[2] = {0.f, 0.f};
;     u32x4 kst[NKL], vst[2];
;     const int ntiles = nkeys >> 6;
;     ...
;     DA_LOAD(0); DA_STORE(0);
;     __syncthreads();
; DI void dense192_item(unsigned char* ws, LAS unsigned char* lds, int b, int h, int q0, int nk) {
;     const size_t rowb = (size_t)b * RB, row0 = rowb + q0;
;     dense_attn_item<192>(lds, (const bf16_t*)(ws + WS_QM) + row0 * 960 + h * 192, 960, (const bf16_t*)(ws + WS_KM) + rowb * 640 + h * 128, 640, (const bf16_t*)(ws + WS_KPE) + rowb * 64,
;                          (const bf16_t*)(ws + WS_VTM) + ((size_t)b * 640 + h * 128) * RB, nk, 0.07216878364870322f * 1.4426950408889634f, (bf16_t*)(ws + WS_YMIX) + row0 * DM + 768 + h * 128);
.LBB0_1146:
	s_mul_hi_u32 s71, s28, 0x66666667
	s_lshr_b32 s71, s71, 4
	s_lshr_b32 s73, s28, 3
	s_mul_i32 s62, s71, 5
	s_sub_u32 s73, s73, s62
	s_and_b32 s62, s28, 7
	s_lshl_b32 s62, s62, 8
	s_mul_i32 s75, s71, 0x900
	s_add_u32 s74, s75, s62
	s_addk_i32 s74, 0x100
	s_mul_i32 s62, s74, 0x780
	s_mul_i32 s63, s73, 0x180
	s_add_u32 s62, s62, s63
	s_add_u32 s62, s62, 0x1a3a0000
	s_add_u32 s10, s50, s62
	s_addc_u32 s11, s51, 0
	s_mul_i32 s62, s75, 0x500
	s_lshl_b32 s63, s73, 8
	s_add_u32 s62, s62, s63
	s_add_u32 s62, s62, 0x1b480000
	s_add_u32 s4, s50, s62
	s_addc_u32 s5, s51, 0
	s_mul_i32 s62, s75, 0x480
	s_add_u32 s62, s62, s63
	s_sub_u32 s76, 0x167ff00, s62
	s_mul_i32 s62, s71, 0x280
	s_lshl_b32 s63, s73, 7
	s_add_u32 s62, s62, s63
	s_mul_i32 s62, s62, 0x1200
	s_add_u32 s62, s62, 0x1bfc0000
	s_add_u32 s8, s50, s62
	s_addc_u32 s9, s51, 0
	s_lshl_b32 s62, s74, 12
	s_lshl_b32 s63, s73, 8
	s_add_u32 s62, s62, s63
	s_add_u32 s62, s62, 0x1d9a0600
	s_add_u32 s20, s50, s62
	s_addc_u32 s21, s51, 0
	s_mov_b32 s22, 0x3dd53b94
	v_mov_b32_e32 v254, s22
	s_mov_b32 s29, 0x41000000
	v_and_b32_e32 v192, 31, v202
	v_bfe_u32 v193, v202, 5, 1
	v_lshrrev_b32_e32 v194, 6, v202
	v_lshl_add_u32 v195, v194, 5, v192
	v_mul_u32_u24_e32 v196, 0x780, v195
	v_lshl_add_u32 v250, v193, 4, v196
	global_load_dwordx4 v[0:3], v250, s[10:11] offset:0
	global_load_dwordx4 v[4:7], v250, s[10:11] offset:32
	global_load_dwordx4 v[8:11], v250, s[10:11] offset:64
	global_load_dwordx4 v[12:15], v250, s[10:11] offset:96
	global_load_dwordx4 v[16:19], v250, s[10:11] offset:128
	global_load_dwordx4 v[20:23], v250, s[10:11] offset:160
	global_load_dwordx4 v[24:27], v250, s[10:11] offset:192
	global_load_dwordx4 v[28:31], v250, s[10:11] offset:224
	global_load_dwordx4 v[32:35], v250, s[10:11] offset:256
	global_load_dwordx4 v[36:39], v250, s[10:11] offset:288
	global_load_dwordx4 v[40:43], v250, s[10:11] offset:320
	global_load_dwordx4 v[44:47], v250, s[10:11] offset:352
	s_mov_b32 s62, 0xaaaaaab
	v_mov_b32_e32 v197, v202
	v_mul_hi_u32 v198, v197, s62
	v_mul_u32_u24_e32 v195, 24, v198
	v_sub_u32_e32 v199, v197, v195
	v_mul_u32_u24_e32 v195, 0x190, v198
	v_lshl_add_u32 v230, v199, 4, v195
	v_cmp_gt_u32_e32 vcc, 16, v199
	v_mul_u32_u24_e32 v195, 0x500, v198
	v_lshlrev_b32_e32 v196, 7, v198
	v_add_u32_e32 v196, s76, v196
	s_nop 1
	v_cndmask_b32_e32 v195, v196, v195, vcc
	v_lshl_add_u32 v224, v199, 4, v195
	v_mov_b32_e32 v195, 0x2000
	v_mov_b32_e32 v196, 0x14000
	v_cndmask_b32_e32 v227, v195, v196, vcc
	v_add_u32_e32 v197, 0x200, v202
	v_mul_hi_u32 v198, v197, s62
	v_mul_u32_u24_e32 v195, 24, v198
	v_sub_u32_e32 v199, v197, v195
	v_mul_u32_u24_e32 v195, 0x190, v198
	v_lshl_add_u32 v231, v199, 4, v195
	v_cmp_gt_u32_e32 vcc, 16, v199
	v_mul_u32_u24_e32 v195, 0x500, v198
	v_lshlrev_b32_e32 v196, 7, v198
	v_add_u32_e32 v196, s76, v196
	s_nop 1
	v_cndmask_b32_e32 v195, v196, v195, vcc
	v_lshl_add_u32 v225, v199, 4, v195
	v_mov_b32_e32 v195, 0x2000
	v_mov_b32_e32 v196, 0x14000
	v_cndmask_b32_e32 v228, v195, v196, vcc
	v_add_u32_e32 v197, 0x400, v202
	v_mul_hi_u32 v198, v197, s62
	v_mul_u32_u24_e32 v195, 24, v198
	v_sub_u32_e32 v199, v197, v195
	v_mul_u32_u24_e32 v195, 0x190, v198
	v_lshl_add_u32 v232, v199, 4, v195
	v_cmp_gt_u32_e32 vcc, 16, v199
	v_mul_u32_u24_e32 v195, 0x500, v198
	v_lshlrev_b32_e32 v196, 7, v198
	v_add_u32_e32 v196, s76, v196
	s_nop 1
	v_cndmask_b32_e32 v195, v196, v195, vcc
	v_lshl_add_u32 v226, v199, 4, v195
	v_mov_b32_e32 v195, 0x2000
	v_mov_b32_e32 v196, 0x14000
	v_cndmask_b32_e32 v229, v195, v196, vcc
	v_mov_b32_e32 v197, v202
	v_lshrrev_b32_e32 v198, 3, v197
	v_and_b32_e32 v199, 7, v197
	v_mul_u32_u24_e32 v195, 0x1200, v198
	v_lshl_add_u32 v233, v199, 4, v195
	v_mul_u32_u24_e32 v195, 0x90, v198
	v_lshl_add_u32 v195, v199, 4, v195
	v_add_u32_e32 v235, 0x12c00, v195
	v_add_u32_e32 v197, 0x200, v202
	v_lshrrev_b32_e32 v198, 3, v197
	v_and_b32_e32 v199, 7, v197
	v_mul_u32_u24_e32 v195, 0x1200, v198
	v_lshl_add_u32 v234, v199, 4, v195
	v_mul_u32_u24_e32 v195, 0x90, v198
	v_lshl_add_u32 v195, v199, 4, v195
	v_add_u32_e32 v236, 0x12c00, v195
	v_mul_u32_u24_e32 v195, 0x190, v192
	v_lshl_add_u32 v237, v193, 4, v195
	v_mul_u32_u24_e32 v195, 0x90, v192
	v_lshl_add_u32 v195, v193, 3, v195
	v_add_u32_e32 v238, 0x12c00, v195
	global_load_dwordx4 v[204:207], v224, s[4:5]
	global_load_dwordx4 v[208:211], v225, s[4:5]
	global_load_dwordx4 v[212:215], v226, s[4:5]
	global_load_dwordx4 v[216:219], v233, s[8:9]
	global_load_dwordx4 v[220:223], v234, s[8:9]
	v_add_u32_e32 v224, v224, v227
	v_add_u32_e32 v225, v225, v228
	v_add_u32_e32 v226, v226, v229
	s_add_u32 s8, s8, 0x80
	s_addc_u32 s9, s9, 0
	v_mov_b32_e32 v48, 0
	v_mov_b32_e32 v49, 0
	v_mov_b32_e32 v50, 0
	v_mov_b32_e32 v51, 0
	v_mov_b32_e32 v52, 0
	v_mov_b32_e32 v53, 0
	v_mov_b32_e32 v54, 0
	v_mov_b32_e32 v55, 0
	v_mov_b32_e32 v56, 0
	v_mov_b32_e32 v57, 0
	v_mov_b32_e32 v58, 0
	v_mov_b32_e32 v59, 0
	v_mov_b32_e32 v60, 0
	v_mov_b32_e32 v61, 0
	v_mov_b32_e32 v62, 0
	v_mov_b32_e32 v63, 0
	v_mov_b32_e32 v64, 0
	v_mov_b32_e32 v65, 0
	v_mov_b32_e32 v66, 0
	v_mov_b32_e32 v67, 0
	v_mov_b32_e32 v68, 0
	v_mov_b32_e32 v69, 0
	v_mov_b32_e32 v70, 0
	v_mov_b32_e32 v71, 0
	v_mov_b32_e32 v72, 0
	v_mov_b32_e32 v73, 0
	v_mov_b32_e32 v74, 0
	v_mov_b32_e32 v75, 0
	v_mov_b32_e32 v76, 0
	v_mov_b32_e32 v77, 0
	v_mov_b32_e32 v78, 0
	v_mov_b32_e32 v79, 0
	v_mov_b32_e32 v80, 0
	v_mov_b32_e32 v81, 0
	v_mov_b32_e32 v82, 0
	v_mov_b32_e32 v83, 0
	v_mov_b32_e32 v84, 0
	v_mov_b32_e32 v85, 0
	v_mov_b32_e32 v86, 0
	v_mov_b32_e32 v87, 0
	v_mov_b32_e32 v88, 0
	v_mov_b32_e32 v89, 0
	v_mov_b32_e32 v90, 0
	v_mov_b32_e32 v91, 0
	v_mov_b32_e32 v92, 0
	v_mov_b32_e32 v93, 0
	v_mov_b32_e32 v94, 0
	v_mov_b32_e32 v95, 0
	v_mov_b32_e32 v96, 0
	v_mov_b32_e32 v97, 0
	v_mov_b32_e32 v98, 0
	v_mov_b32_e32 v99, 0
	v_mov_b32_e32 v100, 0
	v_mov_b32_e32 v101, 0
	v_mov_b32_e32 v102, 0
	v_mov_b32_e32 v103, 0
	v_mov_b32_e32 v104, 0
	v_mov_b32_e32 v105, 0
	v_mov_b32_e32 v106, 0
	v_mov_b32_e32 v107, 0
	v_mov_b32_e32 v108, 0
	v_mov_b32_e32 v109, 0
	v_mov_b32_e32 v110, 0
	v_mov_b32_e32 v111, 0
	v_mov_b32_e32 v242, 0xf149f2ca
	v_mov_b32_e32 v244, 0
	s_waitcnt vmcnt(0)
	v_lshl_add_u32 v195, v194, 5, v192
	v_lshlrev_b32_e32 v195, 12, v195
	v_lshl_add_u32 v250, v193, 3, v195
	ds_write_b128 v230, v[204:207]
	ds_write_b128 v231, v[208:211]
	ds_write_b128 v232, v[212:215]
	ds_write_b128 v235, v[216:219]
	ds_write_b128 v236, v[220:223]
	s_waitcnt lgkmcnt(0)
	global_load_dwordx4 v[204:207], v224, s[4:5]
	global_load_dwordx4 v[208:211], v225, s[4:5]
	global_load_dwordx4 v[212:215], v226, s[4:5]
	global_load_dwordx4 v[216:219], v233, s[8:9]
	global_load_dwordx4 v[220:223], v234, s[8:9]
	s_barrier
; #define LAS __attribute__((address_space(3)))
; template <int DK>
; DI void dense_attn_item(LAS unsigned char* lds, const bf16_t* Qb, int ldq, const bf16_t* Kb, int ldk, const bf16_t* Kpe, const bf16_t* Vt, int nkeys, float sl2, bf16_t* Ob) {
;     ...
;     DA_LOAD(0); DA_STORE(0);
;     __syncthreads();
;     for (int kt = 0; kt < ntiles; ++kt) {
;         const int cur = kt & 1;
;         if (kt + 1 < ntiles) DA_LOAD((kt + 1) * 64);
;         const LAS unsigned char* kb_ = lds + cur * KTILE; const LAS unsigned char* vb_ = lds + 2 * KTILE + cur * VTILE;
; #pragma unroll
;         for (int kc = 0; kc < 2; ++kc) {
;             f32x4 sacc[2][2];
; #pragma unroll
;             for (int kb = 0; kb < 2; ++kb) {
;                 sacc[0][kb] = (f32x4){0.f, 0.f, 0.f, 0.f}; sacc[1][kb] = (f32x4){0.f, 0.f, 0.f, 0.f};
; #pragma unroll
;                 for (int kh = 0; kh < KS / 2; ++kh) {
;                     const bf16x8 k0 = *(const LAS bf16x8*)(kb_ + ((2 * kc + kb) * 16 + r16) * KROW + (2 * kh) * 64 + q4 * 16);
;                     const bf16x8 k1 = *(const LAS bf16x8*)(kb_ + ((2 * kc + kb) * 16 + r16) * KROW + (2 * kh + 1) * 64 + q4 * 16);
;                     __builtin_amdgcn_s_setprio(1);
;                     sacc[0][kb] = MFMA16(k0, qf[0][2 * kh], sacc[0][kb]); sacc[1][kb] = MFMA16(k0, qf[1][2 * kh], sacc[1][kb]);
;                     sacc[0][kb] = MFMA16(k1, qf[0][2 * kh + 1], sacc[0][kb]); sacc[1][kb] = MFMA16(k1, qf[1][2 * kh + 1], sacc[1][kb]);
;                     __builtin_amdgcn_s_setprio(0);
;                 }
;             }
;             bf16x8 pb[2];
; #pragma unroll
;             for (int qg = 0; qg < 2; ++qg) {
;                 float mx = fmaxf(fmaxf(fmaxf(sacc[qg][0][0], sacc[qg][0][1]), fmaxf(sacc[qg][0][2], sacc[qg][0][3])), fmaxf(fmaxf(sacc[qg][1][0], sacc[qg][1][1]), fmaxf(sacc[qg][1][2], sacc[qg][1][3])));
;                 mx = fmaxf(mx, __shfl_xor(mx, 16)); mx = fmaxf(mx, __shfl_xor(mx, 32));
;                 const float mnew = fmaxf(mrun[qg], mx * sl2), alpha = fast_exp2(mrun[qg] - mnew);
;                 mrun[qg] = mnew;
;                 float ps = 0.f;
; #pragma unroll
;                 for (int kb = 0; kb < 2; ++kb)
; #pragma unroll
;                     for (int j = 0; j < 4; ++j) { const float pv = fast_exp2(sacc[qg][kb][j] * sl2 - mnew); sacc[qg][kb][j] = pv; ps += pv; }
	v_mov_b32_e32 v239, v237
	ds_read_b128 v[144:147], v239 offset:0
	ds_read_b128 v[148:151], v239 offset:32
	ds_read_b128 v[152:155], v239 offset:64
	ds_read_b128 v[156:159], v239 offset:96
	ds_read_b128 v[160:163], v239 offset:128
	ds_read_b128 v[164:167], v239 offset:160
	s_waitcnt lgkmcnt(5)
	v_mfma_f32_32x32x16_bf16 v[112:127], v[144:147], v[0:3], 0
	ds_read_b128 v[144:147], v239 offset:192
	s_waitcnt lgkmcnt(5)
	v_mfma_f32_32x32x16_bf16 v[112:127], v[148:151], v[4:7], v[112:127]
	ds_read_b128 v[148:151], v239 offset:224
	s_waitcnt lgkmcnt(5)
	v_mfma_f32_32x32x16_bf16 v[112:127], v[152:155], v[8:11], v[112:127]
	ds_read_b128 v[152:155], v239 offset:256
	s_waitcnt lgkmcnt(5)
	v_mfma_f32_32x32x16_bf16 v[112:127], v[156:159], v[12:15], v[112:127]
	ds_read_b128 v[156:159], v239 offset:288
	s_waitcnt lgkmcnt(5)
	v_mfma_f32_32x32x16_bf16 v[112:127], v[160:163], v[16:19], v[112:127]
	ds_read_b128 v[160:163], v239 offset:320
	s_waitcnt lgkmcnt(5)
	v_mfma_f32_32x32x16_bf16 v[112:127], v[164:167], v[20:23], v[112:127]
	ds_read_b128 v[164:167], v239 offset:352
	s_waitcnt lgkmcnt(5)
	v_mfma_f32_32x32x16_bf16 v[112:127], v[144:147], v[24:27], v[112:127]
	s_waitcnt lgkmcnt(4)
	v_mfma_f32_32x32x16_bf16 v[112:127], v[148:151], v[28:31], v[112:127]
	s_waitcnt lgkmcnt(3)
	v_mfma_f32_32x32x16_bf16 v[112:127], v[152:155], v[32:35], v[112:127]
	s_waitcnt lgkmcnt(2)
	v_mfma_f32_32x32x16_bf16 v[112:127], v[156:159], v[36:39], v[112:127]
	s_waitcnt lgkmcnt(1)
	v_mfma_f32_32x32x16_bf16 v[112:127], v[160:163], v[40:43], v[112:127]
	s_waitcnt lgkmcnt(0)
	v_mfma_f32_32x32x16_bf16 v[112:127], v[164:167], v[44:47], v[112:127]
	s_mov_b32 s23, 0
	s_mov_b32 s27, 0
dn0_top:
	s_add_u32 s57, s27, 1
	s_cmp_eq_u32 s57, 3
	s_cselect_b32 s57, 0, s57
	s_mul_i32 s36, s27, 0x6400
	s_mul_i32 s54, s27, 0x4800
	s_mul_i32 s37, s57, 0x6400
	s_mul_i32 s56, s57, 0x4800
	v_add_u32_e32 v239, s36, v237
	v_add_u32_e32 v240, s37, v237
	v_add_u32_e32 v241, s54, v238
	v_add_u32_e32 v196, s37, v230
	v_add_u32_e32 v197, s37, v231
	v_add_u32_e32 v198, s37, v232
	v_add_u32_e32 v199, s56, v235
	v_add_u32_e32 v200, s56, v236
	v_add_u32_e32 v224, v224, v227
	v_add_u32_e32 v225, v225, v228
	v_add_u32_e32 v226, v226, v229
	s_add_u32 s8, s8, 0x80
	s_addc_u32 s9, s9, 0
	s_waitcnt vmcnt(0)
	ds_write_b128 v196, v[204:207]
	ds_write_b128 v197, v[208:211]
	ds_write_b128 v198, v[212:215]
	ds_write_b128 v199, v[216:219]
	ds_write_b128 v200, v[220:223]
	ds_read_b128 v[144:147], v239 offset:12800
	ds_read_b128 v[148:151], v239 offset:12832
	ds_read_b128 v[152:155], v239 offset:12864
	ds_read_b128 v[156:159], v239 offset:12896
	ds_read_b128 v[160:163], v239 offset:12928
	ds_read_b128 v[164:167], v239 offset:12960
	v_max3_f32 v193, v112, v113, v114
	v_max3_f32 v192, v115, v116, v117
	v_max3_f32 v193, v193, v118, v119
	v_max3_f32 v192, v192, v120, v121
	v_max3_f32 v193, v193, v122, v123
	v_max3_f32 v192, v192, v124, v125
	v_max3_f32 v193, v193, v126, v127
	v_max_f32_e32 v193, v193, v192
	v_mov_b32_e32 v192, v193
	s_nop 1
	s_waitcnt lgkmcnt(5)
	global_load_dwordx4 v[204:207], v224, s[4:5]
	global_load_dwordx4 v[208:211], v225, s[4:5]
	global_load_dwordx4 v[212:215], v226, s[4:5]
	global_load_dwordx4 v[216:219], v233, s[8:9]
	global_load_dwordx4 v[220:223], v234, s[8:9]
	v_mfma_f32_32x32x16_bf16 v[128:143], v[144:147], v[0:3], 0
	v_permlane32_swap_b32_e32 v193, v192
	v_max_f32_e32 v193, v193, v192
	v_mul_f32_e32 v193, s22, v193
	v_max_f32_e32 v192, v242, v193
	v_sub_f32_e32 v193, v192, v242
	ds_read_b128 v[144:147], v239 offset:12992
	s_waitcnt lgkmcnt(5)
	v_mfma_f32_32x32x16_bf16 v[128:143], v[148:151], v[4:7], v[128:143]
	v_cmp_gt_f32_e64 s[68:69], v193, s29
	s_cmp_lg_u64 s[68:69], 0
	s_cselect_b64 s[68:69], -1, 0
	v_cndmask_b32_e64 v192, v242, v192, s[68:69]
	v_sub_f32_e32 v193, v242, v192
	ds_read_b128 v[148:151], v239 offset:13024
	s_waitcnt lgkmcnt(5)
	v_mfma_f32_32x32x16_bf16 v[128:143], v[152:155], v[8:11], v[128:143]
	v_exp_f32_e32 v246, v193
	v_mov_b32_e32 v242, v192
	v_pk_fma_f32 v[112:113], v[112:113], v[254:255], v[192:193] op_sel_hi:[1,0,0] neg_lo:[0,0,1] neg_hi:[0,0,1]
	v_pk_fma_f32 v[114:115], v[114:115], v[254:255], v[192:193] op_sel_hi:[1,0,0] neg_lo:[0,0,1] neg_hi:[0,0,1]
	v_pk_fma_f32 v[116:117], v[116:117], v[254:255], v[192:193] op_sel_hi:[1,0,0] neg_lo:[0,0,1] neg_hi:[0,0,1]
	ds_read_b128 v[152:155], v239 offset:13056
	s_waitcnt lgkmcnt(5)
	v_mfma_f32_32x32x16_bf16 v[128:143], v[156:159], v[12:15], v[128:143]
	v_pk_fma_f32 v[118:119], v[118:119], v[254:255], v[192:193] op_sel_hi:[1,0,0] neg_lo:[0,0,1] neg_hi:[0,0,1]
	v_pk_fma_f32 v[120:121], v[120:121], v[254:255], v[192:193] op_sel_hi:[1,0,0] neg_lo:[0,0,1] neg_hi:[0,0,1]
	v_pk_fma_f32 v[122:123], v[122:123], v[254:255], v[192:193] op_sel_hi:[1,0,0] neg_lo:[0,0,1] neg_hi:[0,0,1]
	v_pk_fma_f32 v[124:125], v[124:125], v[254:255], v[192:193] op_sel_hi:[1,0,0] neg_lo:[0,0,1] neg_hi:[0,0,1]
	v_pk_fma_f32 v[126:127], v[126:127], v[254:255], v[192:193] op_sel_hi:[1,0,0] neg_lo:[0,0,1] neg_hi:[0,0,1]
	ds_read_b128 v[156:159], v239 offset:13088
	s_waitcnt lgkmcnt(5)
	v_mfma_f32_32x32x16_bf16 v[128:143], v[160:163], v[16:19], v[128:143]
	v_exp_f32_e32 v112, v112
	v_exp_f32_e32 v113, v113
	v_exp_f32_e32 v114, v114
	v_exp_f32_e32 v115, v115
	v_exp_f32_e32 v116, v116
	ds_read_b128 v[160:163], v239 offset:13120
	s_waitcnt lgkmcnt(5)
	v_mfma_f32_32x32x16_bf16 v[128:143], v[164:167], v[20:23], v[128:143]
	v_exp_f32_e32 v117, v117
	v_exp_f32_e32 v118, v118
	v_exp_f32_e32 v119, v119
	v_exp_f32_e32 v120, v120
	v_exp_f32_e32 v121, v121
	ds_read_b128 v[164:167], v239 offset:13152
	s_waitcnt lgkmcnt(5)
; template <int DK>
; DI void dense_attn_item(LAS unsigned char* lds, const bf16_t* Qb, int ldq, const bf16_t* Kb, int ldk, const bf16_t* Kpe, const bf16_t* Vt, int nkeys, float sl2, bf16_t* Ob) {
;     ...
;             for (int kb = 0; kb < 2; ++kb) {
;                 sacc[0][kb] = (f32x4){0.f, 0.f, 0.f, 0.f}; sacc[1][kb] = (f32x4){0.f, 0.f, 0.f, 0.f};
; #pragma unroll
;                 for (int kh = 0; kh < KS / 2; ++kh) {
;                     const bf16x8 k0 = *(const LAS bf16x8*)(kb_ + ((2 * kc + kb) * 16 + r16) * KROW + (2 * kh) * 64 + q4 * 16);
;                     const bf16x8 k1 = *(const LAS bf16x8*)(kb_ + ((2 * kc + kb) * 16 + r16) * KROW + (2 * kh + 1) * 64 + q4 * 16);
;                     __builtin_amdgcn_s_setprio(1);
;                     sacc[0][kb] = MFMA16(k0, qf[0][2 * kh], sacc[0][kb]); sacc[1][kb] = MFMA16(k0, qf[1][2 * kh], sacc[1][kb]);
;                     sacc[0][kb] = MFMA16(k1, qf[0][2 * kh + 1], sacc[0][kb]); sacc[1][kb] = MFMA16(k1, qf[1][2 * kh + 1], sacc[1][kb]);
;                     __builtin_amdgcn_s_setprio(0);
;                 }
;             }
;             bf16x8 pb[2];
; #pragma unroll
;             for (int qg = 0; qg < 2; ++qg) {
;                 float mx = fmaxf(fmaxf(fmaxf(sacc[qg][0][0], sacc[qg][0][1]), fmaxf(sacc[qg][0][2], sacc[qg][0][3])), fmaxf(fmaxf(sacc[qg][1][0], sacc[qg][1][1]), fmaxf(sacc[qg][1][2], sacc[qg][1][3])));
;                 mx = fmaxf(mx, __shfl_xor(mx, 16)); mx = fmaxf(mx, __shfl_xor(mx, 32));
;                 const float mnew = fmaxf(mrun[qg], mx * sl2), alpha = fast_exp2(mrun[qg] - mnew);
;                 mrun[qg] = mnew;
;                 float ps = 0.f;
; #pragma unroll
;                 for (int kb = 0; kb < 2; ++kb)
; #pragma unroll
;                     for (int j = 0; j < 4; ++j) { const float pv = fast_exp2(sacc[qg][kb][j] * sl2 - mnew); sacc[qg][kb][j] = pv; ps += pv; }
;                 lsum[qg] = lsum[qg] * alpha + ps;
; #pragma unroll
;                 for (int d = 0; d < 8; ++d) oacc[qg][d] *= alpha;
;                 u32x4 w; w.x = cvt_pk_bf16(sacc[qg][0][0], sacc[qg][0][1]); w.y = cvt_pk_bf16(sacc[qg][0][2], sacc[qg][0][3]);
;                 w.z = cvt_pk_bf16(sacc[qg][1][0], sacc[qg][1][1]); w.w = cvt_pk_bf16(sacc[qg][1][2], sacc[qg][1][3]);
;                 pb[qg] = __builtin_bit_cast(bf16x8, w);
;             }
; #pragma unroll
	v_mfma_f32_32x32x16_bf16 v[128:143], v[144:147], v[24:27], v[128:143]
	v_exp_f32_e32 v122, v122
	v_exp_f32_e32 v123, v123
	v_exp_f32_e32 v124, v124
	v_exp_f32_e32 v125, v125
	v_exp_f32_e32 v126, v126
	ds_read_b64 v[168:169], v241 offset:0
	ds_read_b64 v[170:171], v241 offset:16
	s_waitcnt lgkmcnt(6)
	v_mfma_f32_32x32x16_bf16 v[128:143], v[148:151], v[28:31], v[128:143]
	v_exp_f32_e32 v127, v127
	v_pk_add_f32 v[196:197], v[112:113], v[114:115]
	v_pk_add_f32 v[198:199], v[116:117], v[118:119]
	v_pk_add_f32 v[196:197], v[196:197], v[120:121]
	v_pk_add_f32 v[198:199], v[198:199], v[122:123]
	ds_read_b64 v[172:173], v241 offset:32
	ds_read_b64 v[174:175], v241 offset:48
	s_waitcnt lgkmcnt(7)
	v_mfma_f32_32x32x16_bf16 v[128:143], v[152:155], v[32:35], v[128:143]
	v_pk_add_f32 v[196:197], v[196:197], v[124:125]
	v_pk_add_f32 v[198:199], v[198:199], v[126:127]
	v_pk_add_f32 v[196:197], v[196:197], v[198:199]
	v_add_f32_e32 v193, v196, v197
	v_fma_f32 v244, v244, v246, v193
	ds_read_b64 v[176:177], v241 offset:4608
	ds_read_b64 v[178:179], v241 offset:4624
	s_waitcnt lgkmcnt(8)
	v_mfma_f32_32x32x16_bf16 v[128:143], v[156:159], v[36:39], v[128:143]
	v_cvt_pk_bf16_f32 v184, v112, v113
	v_cvt_pk_bf16_f32 v185, v114, v115
	v_cvt_pk_bf16_f32 v186, v116, v117
	v_cvt_pk_bf16_f32 v187, v118, v119
	v_cvt_pk_bf16_f32 v188, v120, v121
	ds_read_b64 v[180:181], v241 offset:4640
	ds_read_b64 v[182:183], v241 offset:4656
	s_waitcnt lgkmcnt(9)
	v_mfma_f32_32x32x16_bf16 v[128:143], v[160:163], v[40:43], v[128:143]
	v_cvt_pk_bf16_f32 v189, v122, v123
	v_cvt_pk_bf16_f32 v190, v124, v125
	v_cvt_pk_bf16_f32 v191, v126, v127
	s_waitcnt lgkmcnt(8)
	v_mfma_f32_32x32x16_bf16 v[128:143], v[164:167], v[44:47], v[128:143]
	s_mov_b64 vcc, s[68:69]
	s_cbranch_vccz dn0_nr1
	v_pk_mul_f32 v[48:49], v[48:49], v[246:247] op_sel_hi:[1,0]
	v_pk_mul_f32 v[50:51], v[50:51], v[246:247] op_sel_hi:[1,0]
	v_pk_mul_f32 v[52:53], v[52:53], v[246:247] op_sel_hi:[1,0]
	v_pk_mul_f32 v[54:55], v[54:55], v[246:247] op_sel_hi:[1,0]
	v_pk_mul_f32 v[56:57], v[56:57], v[246:247] op_sel_hi:[1,0]
	v_pk_mul_f32 v[58:59], v[58:59], v[246:247] op_sel_hi:[1,0]
	v_pk_mul_f32 v[60:61], v[60:61], v[246:247] op_sel_hi:[1,0]
	v_pk_mul_f32 v[62:63], v[62:63], v[246:247] op_sel_hi:[1,0]
	s_waitcnt lgkmcnt(6)
	v_mfma_f32_32x32x16_bf16 v[48:63], v[168:171], v[184:187], v[48:63]
	v_pk_mul_f32 v[64:65], v[64:65], v[246:247] op_sel_hi:[1,0]
	v_pk_mul_f32 v[66:67], v[66:67], v[246:247] op_sel_hi:[1,0]
	v_pk_mul_f32 v[68:69], v[68:69], v[246:247] op_sel_hi:[1,0]
	v_pk_mul_f32 v[70:71], v[70:71], v[246:247] op_sel_hi:[1,0]
	ds_read_b64 v[168:169], v241 offset:9216
	ds_read_b64 v[170:171], v241 offset:9232
	s_waitcnt lgkmcnt(6)
	v_mfma_f32_32x32x16_bf16 v[48:63], v[172:175], v[188:191], v[48:63]
	v_pk_mul_f32 v[72:73], v[72:73], v[246:247] op_sel_hi:[1,0]
	v_pk_mul_f32 v[74:75], v[74:75], v[246:247] op_sel_hi:[1,0]
	v_pk_mul_f32 v[76:77], v[76:77], v[246:247] op_sel_hi:[1,0]
	v_pk_mul_f32 v[78:79], v[78:79], v[246:247] op_sel_hi:[1,0]
	ds_read_b64 v[172:173], v241 offset:9248
	ds_read_b64 v[174:175], v241 offset:9264
	s_waitcnt lgkmcnt(6)
	v_mfma_f32_32x32x16_bf16 v[64:79], v[176:179], v[184:187], v[64:79]
	v_pk_mul_f32 v[80:81], v[80:81], v[246:247] op_sel_hi:[1,0]
	v_pk_mul_f32 v[82:83], v[82:83], v[246:247] op_sel_hi:[1,0]
	v_pk_mul_f32 v[84:85], v[84:85], v[246:247] op_sel_hi:[1,0]
	v_pk_mul_f32 v[86:87], v[86:87], v[246:247] op_sel_hi:[1,0]
	ds_read_b64 v[176:177], v241 offset:13824
	ds_read_b64 v[178:179], v241 offset:13840
	s_waitcnt lgkmcnt(6)
	v_mfma_f32_32x32x16_bf16 v[64:79], v[180:183], v[188:191], v[64:79]
	v_pk_mul_f32 v[88:89], v[88:89], v[246:247] op_sel_hi:[1,0]
	v_pk_mul_f32 v[90:91], v[90:91], v[246:247] op_sel_hi:[1,0]
	v_pk_mul_f32 v[92:93], v[92:93], v[246:247] op_sel_hi:[1,0]
	v_pk_mul_f32 v[94:95], v[94:95], v[246:247] op_sel_hi:[1,0]
	ds_read_b64 v[180:181], v241 offset:13856
	ds_read_b64 v[182:183], v241 offset:13872
	s_waitcnt lgkmcnt(6)
	v_mfma_f32_32x32x16_bf16 v[80:95], v[168:171], v[184:187], v[80:95]
	v_pk_mul_f32 v[96:97], v[96:97], v[246:247] op_sel_hi:[1,0]
	v_pk_mul_f32 v[98:99], v[98:99], v[246:247] op_sel_hi:[1,0]
	v_pk_mul_f32 v[100:101], v[100:101], v[246:247] op_sel_hi:[1,0]
	v_pk_mul_f32 v[102:103], v[102:103], v[246:247] op_sel_hi:[1,0]
	s_nop 1
	s_waitcnt lgkmcnt(4)
	v_mfma_f32_32x32x16_bf16 v[80:95], v[172:175], v[188:191], v[80:95]
	v_pk_mul_f32 v[104:105], v[104:105], v[246:247] op_sel_hi:[1,0]
	v_pk_mul_f32 v[106:107], v[106:107], v[246:247] op_sel_hi:[1,0]
	v_pk_mul_f32 v[108:109], v[108:109], v[246:247] op_sel_hi:[1,0]
	v_pk_mul_f32 v[110:111], v[110:111], v[246:247] op_sel_hi:[1,0]
	s_nop 1
	s_waitcnt lgkmcnt(2)
	v_mfma_f32_32x32x16_bf16 v[96:111], v[176:179], v[184:187], v[96:111]
	s_waitcnt lgkmcnt(0)
	v_mfma_f32_32x32x16_bf16 v[96:111], v[180:183], v[188:191], v[96:111]
	s_branch dn0_jn1
dn0_nr1:
	s_nop 1
	s_waitcnt lgkmcnt(6)
	v_mfma_f32_32x32x16_bf16 v[48:63], v[168:171], v[184:187], v[48:63]
	ds_read_b64 v[168:169], v241 offset:9216
	ds_read_b64 v[170:171], v241 offset:9232
	s_waitcnt lgkmcnt(6)
	v_mfma_f32_32x32x16_bf16 v[48:63], v[172:175], v[188:191], v[48:63]
	ds_read_b64 v[172:173], v241 offset:9248
	ds_read_b64 v[174:175], v241 offset:9264
	s_waitcnt lgkmcnt(6)
	v_mfma_f32_32x32x16_bf16 v[64:79], v[176:179], v[184:187], v[64:79]
	ds_read_b64 v[176:177], v241 offset:13824
	ds_read_b64 v[178:179], v241 offset:13840
	s_waitcnt lgkmcnt(6)
	v_mfma_f32_32x32x16_bf16 v[64:79], v[180:183], v[188:191], v[64:79]
	ds_read_b64 v[180:181], v241 offset:13856
	ds_read_b64 v[182:183], v241 offset:13872
	s_waitcnt lgkmcnt(6)
	v_mfma_f32_32x32x16_bf16 v[80:95], v[168:171], v[184:187], v[80:95]
	s_waitcnt lgkmcnt(4)
	v_mfma_f32_32x32x16_bf16 v[80:95], v[172:175], v[188:191], v[80:95]
	s_waitcnt lgkmcnt(2)
	v_mfma_f32_32x32x16_bf16 v[96:111], v[176:179], v[184:187], v[96:111]
	s_waitcnt lgkmcnt(0)
	v_mfma_f32_32x32x16_bf16 v[96:111], v[180:183], v[188:191], v[96:111]
; template <int DK>
; DI void dense_attn_item(LAS unsigned char* lds, const bf16_t* Qb, int ldq, const bf16_t* Kb, int ldk, const bf16_t* Kpe, const bf16_t* Vt, int nkeys, float sl2, bf16_t* Ob) {
;     ...
;     for (int kt = 0; kt < ntiles; ++kt) {
;         const int cur = kt & 1;
;         if (kt + 1 < ntiles) DA_LOAD((kt + 1) * 64);
;         const LAS unsigned char* kb_ = lds + cur * KTILE; const LAS unsigned char* vb_ = lds + 2 * KTILE + cur * VTILE;
; #pragma unroll
;         for (int kc = 0; kc < 2; ++kc) {
;             f32x4 sacc[2][2];
; #pragma unroll
;             for (int kb = 0; kb < 2; ++kb) {
;                 sacc[0][kb] = (f32x4){0.f, 0.f, 0.f, 0.f}; sacc[1][kb] = (f32x4){0.f, 0.f, 0.f, 0.f};
; #pragma unroll
;                 for (int kh = 0; kh < KS / 2; ++kh) {
;                     const bf16x8 k0 = *(const LAS bf16x8*)(kb_ + ((2 * kc + kb) * 16 + r16) * KROW + (2 * kh) * 64 + q4 * 16);
;                     const bf16x8 k1 = *(const LAS bf16x8*)(kb_ + ((2 * kc + kb) * 16 + r16) * KROW + (2 * kh + 1) * 64 + q4 * 16);
;                     __builtin_amdgcn_s_setprio(1);
;                     sacc[0][kb] = MFMA16(k0, qf[0][2 * kh], sacc[0][kb]); sacc[1][kb] = MFMA16(k0, qf[1][2 * kh], sacc[1][kb]);
;                     sacc[0][kb] = MFMA16(k1, qf[0][2 * kh + 1], sacc[0][kb]); sacc[1][kb] = MFMA16(k1, qf[1][2 * kh + 1], sacc[1][kb]);
;                     __builtin_amdgcn_s_setprio(0);
;                 }
;             }
;             bf16x8 pb[2];
; #pragma unroll
;             for (int qg = 0; qg < 2; ++qg) {
;                 float mx = fmaxf(fmaxf(fmaxf(sacc[qg][0][0], sacc[qg][0][1]), fmaxf(sacc[qg][0][2], sacc[qg][0][3])), fmaxf(fmaxf(sacc[qg][1][0], sacc[qg][1][1]), fmaxf(sacc[qg][1][2], sacc[qg][1][3])));
;                 mx = fmaxf(mx, __shfl_xor(mx, 16)); mx = fmaxf(mx, __shfl_xor(mx, 32));
;                 const float mnew = fmaxf(mrun[qg], mx * sl2), alpha = fast_exp2(mrun[qg] - mnew);
;                 mrun[qg] = mnew;
;                 float ps = 0.f;
; #pragma unroll
;                 for (int kb = 0; kb < 2; ++kb)
; #pragma unroll
;                     for (int j = 0; j < 4; ++j) { const float pv = fast_exp2(sacc[qg][kb][j] * sl2 - mnew); sacc[qg][kb][j] = pv; ps += pv; }
;                 lsum[qg] = lsum[qg] * alpha + ps;
; #pragma unroll
;                 for (int d = 0; d < 8; ++d) oacc[qg][d] *= alpha;
dn0_jn1:
	s_waitcnt lgkmcnt(0)
	s_barrier
	ds_read_b128 v[144:147], v240 offset:0
	ds_read_b128 v[148:151], v240 offset:32
	ds_read_b128 v[152:155], v240 offset:64
	ds_read_b128 v[156:159], v240 offset:96
	ds_read_b128 v[160:163], v240 offset:128
	ds_read_b128 v[164:167], v240 offset:160
	v_max3_f32 v193, v128, v129, v130
	v_max3_f32 v192, v131, v132, v133
	v_max3_f32 v193, v193, v134, v135
	v_max3_f32 v192, v192, v136, v137
	v_max3_f32 v193, v193, v138, v139
	v_max3_f32 v192, v192, v140, v141
	v_max3_f32 v193, v193, v142, v143
	v_max_f32_e32 v193, v193, v192
	v_mov_b32_e32 v192, v193
	s_nop 1
	s_waitcnt lgkmcnt(5)
	v_mfma_f32_32x32x16_bf16 v[112:127], v[144:147], v[0:3], 0
	v_permlane32_swap_b32_e32 v193, v192
	v_max_f32_e32 v193, v193, v192
	v_mul_f32_e32 v193, s22, v193
	v_max_f32_e32 v192, v242, v193
	v_sub_f32_e32 v193, v192, v242
	ds_read_b128 v[144:147], v240 offset:192
	s_waitcnt lgkmcnt(5)
	v_mfma_f32_32x32x16_bf16 v[112:127], v[148:151], v[4:7], v[112:127]
	v_cmp_gt_f32_e64 s[68:69], v193, s29
	s_cmp_lg_u64 s[68:69], 0
	s_cselect_b64 s[68:69], -1, 0
	v_cndmask_b32_e64 v192, v242, v192, s[68:69]
	v_sub_f32_e32 v193, v242, v192
	ds_read_b128 v[148:151], v240 offset:224
	s_waitcnt lgkmcnt(5)
	v_mfma_f32_32x32x16_bf16 v[112:127], v[152:155], v[8:11], v[112:127]
	v_exp_f32_e32 v246, v193
	v_mov_b32_e32 v242, v192
	v_pk_fma_f32 v[128:129], v[128:129], v[254:255], v[192:193] op_sel_hi:[1,0,0] neg_lo:[0,0,1] neg_hi:[0,0,1]
	v_pk_fma_f32 v[130:131], v[130:131], v[254:255], v[192:193] op_sel_hi:[1,0,0] neg_lo:[0,0,1] neg_hi:[0,0,1]
	v_pk_fma_f32 v[132:133], v[132:133], v[254:255], v[192:193] op_sel_hi:[1,0,0] neg_lo:[0,0,1] neg_hi:[0,0,1]
	ds_read_b128 v[152:155], v240 offset:256
	s_waitcnt lgkmcnt(5)
	v_mfma_f32_32x32x16_bf16 v[112:127], v[156:159], v[12:15], v[112:127]
	v_pk_fma_f32 v[134:135], v[134:135], v[254:255], v[192:193] op_sel_hi:[1,0,0] neg_lo:[0,0,1] neg_hi:[0,0,1]
	v_pk_fma_f32 v[136:137], v[136:137], v[254:255], v[192:193] op_sel_hi:[1,0,0] neg_lo:[0,0,1] neg_hi:[0,0,1]
	v_pk_fma_f32 v[138:139], v[138:139], v[254:255], v[192:193] op_sel_hi:[1,0,0] neg_lo:[0,0,1] neg_hi:[0,0,1]
	v_pk_fma_f32 v[140:141], v[140:141], v[254:255], v[192:193] op_sel_hi:[1,0,0] neg_lo:[0,0,1] neg_hi:[0,0,1]
	v_pk_fma_f32 v[142:143], v[142:143], v[254:255], v[192:193] op_sel_hi:[1,0,0] neg_lo:[0,0,1] neg_hi:[0,0,1]
	ds_read_b128 v[156:159], v240 offset:288
	s_waitcnt lgkmcnt(5)
	v_mfma_f32_32x32x16_bf16 v[112:127], v[160:163], v[16:19], v[112:127]
	v_exp_f32_e32 v128, v128
	v_exp_f32_e32 v129, v129
	v_exp_f32_e32 v130, v130
	v_exp_f32_e32 v131, v131
	v_exp_f32_e32 v132, v132
	ds_read_b128 v[160:163], v240 offset:320
	s_waitcnt lgkmcnt(5)
	v_mfma_f32_32x32x16_bf16 v[112:127], v[164:167], v[20:23], v[112:127]
	v_exp_f32_e32 v133, v133
	v_exp_f32_e32 v134, v134
	v_exp_f32_e32 v135, v135
	v_exp_f32_e32 v136, v136
	v_exp_f32_e32 v137, v137
	ds_read_b128 v[164:167], v240 offset:352
	s_waitcnt lgkmcnt(5)
	v_mfma_f32_32x32x16_bf16 v[112:127], v[144:147], v[24:27], v[112:127]
	v_exp_f32_e32 v138, v138
	v_exp_f32_e32 v139, v139
	v_exp_f32_e32 v140, v140
	v_exp_f32_e32 v141, v141
	v_exp_f32_e32 v142, v142
	ds_read_b64 v[168:169], v241 offset:64
	ds_read_b64 v[170:171], v241 offset:80
	s_waitcnt lgkmcnt(6)
	v_mfma_f32_32x32x16_bf16 v[112:127], v[148:151], v[28:31], v[112:127]
	v_exp_f32_e32 v143, v143
	v_pk_add_f32 v[196:197], v[128:129], v[130:131]
	v_pk_add_f32 v[198:199], v[132:133], v[134:135]
	v_pk_add_f32 v[196:197], v[196:197], v[136:137]
	v_pk_add_f32 v[198:199], v[198:199], v[138:139]
	ds_read_b64 v[172:173], v241 offset:96
	ds_read_b64 v[174:175], v241 offset:112
	s_waitcnt lgkmcnt(7)
	v_mfma_f32_32x32x16_bf16 v[112:127], v[152:155], v[32:35], v[112:127]
	v_pk_add_f32 v[196:197], v[196:197], v[140:141]
	v_pk_add_f32 v[198:199], v[198:199], v[142:143]
	v_pk_add_f32 v[196:197], v[196:197], v[198:199]
	v_add_f32_e32 v193, v196, v197
	v_fma_f32 v244, v244, v246, v193
	ds_read_b64 v[176:177], v241 offset:4672
	ds_read_b64 v[178:179], v241 offset:4688
	s_waitcnt lgkmcnt(8)
	v_mfma_f32_32x32x16_bf16 v[112:127], v[156:159], v[36:39], v[112:127]
	v_cvt_pk_bf16_f32 v184, v128, v129
	v_cvt_pk_bf16_f32 v185, v130, v131
	v_cvt_pk_bf16_f32 v186, v132, v133
	v_cvt_pk_bf16_f32 v187, v134, v135
	v_cvt_pk_bf16_f32 v188, v136, v137
	ds_read_b64 v[180:181], v241 offset:4704
	ds_read_b64 v[182:183], v241 offset:4720
	s_waitcnt lgkmcnt(9)
	v_mfma_f32_32x32x16_bf16 v[112:127], v[160:163], v[40:43], v[112:127]
	v_cvt_pk_bf16_f32 v189, v138, v139
	v_cvt_pk_bf16_f32 v190, v140, v141
	v_cvt_pk_bf16_f32 v191, v142, v143
	s_waitcnt lgkmcnt(8)
	v_mfma_f32_32x32x16_bf16 v[112:127], v[164:167], v[44:47], v[112:127]
	s_mov_b64 vcc, s[68:69]
	s_cbranch_vccz dn0_nr2
; #define LAS __attribute__((address_space(3)))
; #define MFMA16(a, b, c) __builtin_amdgcn_mfma_f32_16x16x32_bf16((a), (b), (c), 0, 0, 0)
; template <int DK>
; DI void dense_attn_item(LAS unsigned char* lds, const bf16_t* Qb, int ldq, const bf16_t* Kb, int ldk, const bf16_t* Kpe, const bf16_t* Vt, int nkeys, float sl2, bf16_t* Ob) {
;     ...
; #pragma unroll
;             for (int dh = 0; dh < 4; ++dh) {
;                 bf16x8 vfr[2];
; #pragma unroll
;                 for (int d4 = 0; d4 < 2; ++d4) {
;                     const int d = dh * 2 + d4;
;                     const u32x2 lo = *(const LAS u32x2*)(vb_ + (d * 16 + r16) * VROW + (kc * 32 + q4 * 4) * 2);
;                     const u32x2 hi = *(const LAS u32x2*)(vb_ + (d * 16 + r16) * VROW + (kc * 32 + 16 + q4 * 4) * 2);
;                     u32x4 w; w.x = lo.x; w.y = lo.y; w.z = hi.x; w.w = hi.y;
;                     vfr[d4] = __builtin_bit_cast(bf16x8, w);
;                 }
;                 __builtin_amdgcn_s_setprio(1);
; #pragma unroll
;                 for (int d4 = 0; d4 < 2; ++d4) { const int d = dh * 2 + d4; oacc[0][d] = MFMA16(vfr[d4], pb[0], oacc[0][d]); oacc[1][d] = MFMA16(vfr[d4], pb[1], oacc[1][d]); }
;                 __builtin_amdgcn_s_setprio(0);
;             }
	v_pk_mul_f32 v[48:49], v[48:49], v[246:247] op_sel_hi:[1,0]
	v_pk_mul_f32 v[50:51], v[50:51], v[246:247] op_sel_hi:[1,0]
	v_pk_mul_f32 v[52:53], v[52:53], v[246:247] op_sel_hi:[1,0]
	v_pk_mul_f32 v[54:55], v[54:55], v[246:247] op_sel_hi:[1,0]
	v_pk_mul_f32 v[56:57], v[56:57], v[246:247] op_sel_hi:[1,0]
	v_pk_mul_f32 v[58:59], v[58:59], v[246:247] op_sel_hi:[1,0]
	v_pk_mul_f32 v[60:61], v[60:61], v[246:247] op_sel_hi:[1,0]
	v_pk_mul_f32 v[62:63], v[62:63], v[246:247] op_sel_hi:[1,0]
	s_waitcnt lgkmcnt(6)
	v_mfma_f32_32x32x16_bf16 v[48:63], v[168:171], v[184:187], v[48:63]
	v_pk_mul_f32 v[64:65], v[64:65], v[246:247] op_sel_hi:[1,0]
	v_pk_mul_f32 v[66:67], v[66:67], v[246:247] op_sel_hi:[1,0]
	v_pk_mul_f32 v[68:69], v[68:69], v[246:247] op_sel_hi:[1,0]
	v_pk_mul_f32 v[70:71], v[70:71], v[246:247] op_sel_hi:[1,0]
	ds_read_b64 v[168:169], v241 offset:9280
	ds_read_b64 v[170:171], v241 offset:9296
	s_waitcnt lgkmcnt(6)
	v_mfma_f32_32x32x16_bf16 v[48:63], v[172:175], v[188:191], v[48:63]
	v_pk_mul_f32 v[72:73], v[72:73], v[246:247] op_sel_hi:[1,0]
	v_pk_mul_f32 v[74:75], v[74:75], v[246:247] op_sel_hi:[1,0]
	v_pk_mul_f32 v[76:77], v[76:77], v[246:247] op_sel_hi:[1,0]
	v_pk_mul_f32 v[78:79], v[78:79], v[246:247] op_sel_hi:[1,0]
	ds_read_b64 v[172:173], v241 offset:9312
	ds_read_b64 v[174:175], v241 offset:9328
	s_waitcnt lgkmcnt(6)
	v_mfma_f32_32x32x16_bf16 v[64:79], v[176:179], v[184:187], v[64:79]
	v_pk_mul_f32 v[80:81], v[80:81], v[246:247] op_sel_hi:[1,0]
	v_pk_mul_f32 v[82:83], v[82:83], v[246:247] op_sel_hi:[1,0]
	v_pk_mul_f32 v[84:85], v[84:85], v[246:247] op_sel_hi:[1,0]
	v_pk_mul_f32 v[86:87], v[86:87], v[246:247] op_sel_hi:[1,0]
	ds_read_b64 v[176:177], v241 offset:13888
	ds_read_b64 v[178:179], v241 offset:13904
	s_waitcnt lgkmcnt(6)
	v_mfma_f32_32x32x16_bf16 v[64:79], v[180:183], v[188:191], v[64:79]
	v_pk_mul_f32 v[88:89], v[88:89], v[246:247] op_sel_hi:[1,0]
	v_pk_mul_f32 v[90:91], v[90:91], v[246:247] op_sel_hi:[1,0]
	v_pk_mul_f32 v[92:93], v[92:93], v[246:247] op_sel_hi:[1,0]
	v_pk_mul_f32 v[94:95], v[94:95], v[246:247] op_sel_hi:[1,0]
	ds_read_b64 v[180:181], v241 offset:13920
	ds_read_b64 v[182:183], v241 offset:13936
	s_waitcnt lgkmcnt(6)
	v_mfma_f32_32x32x16_bf16 v[80:95], v[168:171], v[184:187], v[80:95]
	v_pk_mul_f32 v[96:97], v[96:97], v[246:247] op_sel_hi:[1,0]
	v_pk_mul_f32 v[98:99], v[98:99], v[246:247] op_sel_hi:[1,0]
	v_pk_mul_f32 v[100:101], v[100:101], v[246:247] op_sel_hi:[1,0]
	v_pk_mul_f32 v[102:103], v[102:103], v[246:247] op_sel_hi:[1,0]
	s_nop 1
	s_waitcnt lgkmcnt(4)
	v_mfma_f32_32x32x16_bf16 v[80:95], v[172:175], v[188:191], v[80:95]
	v_pk_mul_f32 v[104:105], v[104:105], v[246:247] op_sel_hi:[1,0]
	v_pk_mul_f32 v[106:107], v[106:107], v[246:247] op_sel_hi:[1,0]
	v_pk_mul_f32 v[108:109], v[108:109], v[246:247] op_sel_hi:[1,0]
	v_pk_mul_f32 v[110:111], v[110:111], v[246:247] op_sel_hi:[1,0]
	s_nop 1
	s_waitcnt lgkmcnt(2)
	v_mfma_f32_32x32x16_bf16 v[96:111], v[176:179], v[184:187], v[96:111]
	s_waitcnt lgkmcnt(0)
	v_mfma_f32_32x32x16_bf16 v[96:111], v[180:183], v[188:191], v[96:111]
	s_branch dn0_jn2
dn0_nr2:
	s_nop 1
	s_waitcnt lgkmcnt(6)
	v_mfma_f32_32x32x16_bf16 v[48:63], v[168:171], v[184:187], v[48:63]
	ds_read_b64 v[168:169], v241 offset:9280
	ds_read_b64 v[170:171], v241 offset:9296
	s_waitcnt lgkmcnt(6)
	v_mfma_f32_32x32x16_bf16 v[48:63], v[172:175], v[188:191], v[48:63]
	ds_read_b64 v[172:173], v241 offset:9312
	ds_read_b64 v[174:175], v241 offset:9328
	s_waitcnt lgkmcnt(6)
	v_mfma_f32_32x32x16_bf16 v[64:79], v[176:179], v[184:187], v[64:79]
	ds_read_b64 v[176:177], v241 offset:13888
	ds_read_b64 v[178:179], v241 offset:13904
	s_waitcnt lgkmcnt(6)
	v_mfma_f32_32x32x16_bf16 v[64:79], v[180:183], v[188:191], v[64:79]
	ds_read_b64 v[180:181], v241 offset:13920
	ds_read_b64 v[182:183], v241 offset:13936
	s_waitcnt lgkmcnt(6)
	v_mfma_f32_32x32x16_bf16 v[80:95], v[168:171], v[184:187], v[80:95]
	s_waitcnt lgkmcnt(4)
	v_mfma_f32_32x32x16_bf16 v[80:95], v[172:175], v[188:191], v[80:95]
	s_waitcnt lgkmcnt(2)
	v_mfma_f32_32x32x16_bf16 v[96:111], v[176:179], v[184:187], v[96:111]
	s_waitcnt lgkmcnt(0)
	v_mfma_f32_32x32x16_bf16 v[96:111], v[180:183], v[188:191], v[96:111]
; #define LAS __attribute__((address_space(3)))
; DI unsigned xb_add(unsigned* p, unsigned v) { return __hip_atomic_fetch_add(p, v, __ATOMIC_RELAXED, __HIP_MEMORY_SCOPE_AGENT); }
; DI void st_bf16x4(bf16_t* p, f32x4 v) { u32x2 w; w.x = cvt_pk_bf16(v[0], v[1]); w.y = cvt_pk_bf16(v[2], v[3]); *(u32x2*)p = w; }
; DI int next_item(unsigned* ctr, volatile LAS int* slot) {
;     __syncthreads();
;     if (threadIdx.x == 0) *slot = (int)xb_add(ctr, 1u);
;     __syncthreads();
; template <int DK>
; DI void dense_attn_item(LAS unsigned char* lds, const bf16_t* Qb, int ldq, const bf16_t* Kb, int ldk, const bf16_t* Kpe, const bf16_t* Vt, int nkeys, float sl2, bf16_t* Ob) {
;     ...
;         if (kt + 1 < ntiles) DA_STORE(cur ^ 1);
;         __syncthreads();
;     }
; #pragma unroll
;     for (int qg = 0; qg < 2; ++qg) {
;         float l = lsum[qg]; l += __shfl_xor(l, 16); l += __shfl_xor(l, 32);
;         const float inv = 1.f / l;
;         bf16_t* op = Ob + (size_t)(wid * 32 + qg * 16 + r16) * DM + q4 * 4;
; #pragma unroll
;         for (int d = 0; d < 8; ++d) st_bf16x4(op + d * 16, oacc[qg][d] * inv);
;     }
dn0_jn2:
	s_mov_b32 s27, s57
	s_add_u32 s23, s23, 1
	s_cmp_lt_u32 s23, 36
	s_cbranch_scc1 dn0_top
	s_waitcnt vmcnt(0) lgkmcnt(0)
	v_mov_b32_e32 v193, v244
	v_mov_b32_e32 v192, v244
	s_nop 1
	v_permlane32_swap_b32_e32 v193, v192
	v_add_f32_e32 v193, v193, v192
	v_rcp_f32_e32 v192, v193
	s_nop 0
	v_fma_f32 v193, -v193, v192, 1.0
	v_fma_f32 v246, v193, v192, v192
	v_pk_mul_f32 v[48:49], v[48:49], v[246:247] op_sel_hi:[1,0]
	v_pk_mul_f32 v[50:51], v[50:51], v[246:247] op_sel_hi:[1,0]
	v_cvt_pk_bf16_f32 v48, v48, v49
	v_cvt_pk_bf16_f32 v49, v50, v51
	global_store_dwordx2 v250, v[48:49], s[20:21] offset:0
	v_pk_mul_f32 v[52:53], v[52:53], v[246:247] op_sel_hi:[1,0]
	v_pk_mul_f32 v[54:55], v[54:55], v[246:247] op_sel_hi:[1,0]
	v_cvt_pk_bf16_f32 v52, v52, v53
	v_cvt_pk_bf16_f32 v53, v54, v55
	global_store_dwordx2 v250, v[52:53], s[20:21] offset:16
	v_pk_mul_f32 v[56:57], v[56:57], v[246:247] op_sel_hi:[1,0]
	v_pk_mul_f32 v[58:59], v[58:59], v[246:247] op_sel_hi:[1,0]
	v_cvt_pk_bf16_f32 v56, v56, v57
	v_cvt_pk_bf16_f32 v57, v58, v59
	global_store_dwordx2 v250, v[56:57], s[20:21] offset:32
	v_pk_mul_f32 v[60:61], v[60:61], v[246:247] op_sel_hi:[1,0]
	v_pk_mul_f32 v[62:63], v[62:63], v[246:247] op_sel_hi:[1,0]
	v_cvt_pk_bf16_f32 v60, v60, v61
	v_cvt_pk_bf16_f32 v61, v62, v63
	global_store_dwordx2 v250, v[60:61], s[20:21] offset:48
	v_pk_mul_f32 v[64:65], v[64:65], v[246:247] op_sel_hi:[1,0]
	v_pk_mul_f32 v[66:67], v[66:67], v[246:247] op_sel_hi:[1,0]
	v_cvt_pk_bf16_f32 v64, v64, v65
	v_cvt_pk_bf16_f32 v65, v66, v67
	global_store_dwordx2 v250, v[64:65], s[20:21] offset:64
	v_pk_mul_f32 v[68:69], v[68:69], v[246:247] op_sel_hi:[1,0]
	v_pk_mul_f32 v[70:71], v[70:71], v[246:247] op_sel_hi:[1,0]
	v_cvt_pk_bf16_f32 v68, v68, v69
	v_cvt_pk_bf16_f32 v69, v70, v71
	global_store_dwordx2 v250, v[68:69], s[20:21] offset:80
	v_pk_mul_f32 v[72:73], v[72:73], v[246:247] op_sel_hi:[1,0]
	v_pk_mul_f32 v[74:75], v[74:75], v[246:247] op_sel_hi:[1,0]
	v_cvt_pk_bf16_f32 v72, v72, v73
	v_cvt_pk_bf16_f32 v73, v74, v75
	global_store_dwordx2 v250, v[72:73], s[20:21] offset:96
	v_pk_mul_f32 v[76:77], v[76:77], v[246:247] op_sel_hi:[1,0]
	v_pk_mul_f32 v[78:79], v[78:79], v[246:247] op_sel_hi:[1,0]
	v_cvt_pk_bf16_f32 v76, v76, v77
	v_cvt_pk_bf16_f32 v77, v78, v79
	global_store_dwordx2 v250, v[76:77], s[20:21] offset:112
	v_pk_mul_f32 v[80:81], v[80:81], v[246:247] op_sel_hi:[1,0]
	v_pk_mul_f32 v[82:83], v[82:83], v[246:247] op_sel_hi:[1,0]
	v_cvt_pk_bf16_f32 v80, v80, v81
	v_cvt_pk_bf16_f32 v81, v82, v83
	global_store_dwordx2 v250, v[80:81], s[20:21] offset:128
	v_pk_mul_f32 v[84:85], v[84:85], v[246:247] op_sel_hi:[1,0]
	v_pk_mul_f32 v[86:87], v[86:87], v[246:247] op_sel_hi:[1,0]
	v_cvt_pk_bf16_f32 v84, v84, v85
	v_cvt_pk_bf16_f32 v85, v86, v87
	global_store_dwordx2 v250, v[84:85], s[20:21] offset:144
	v_pk_mul_f32 v[88:89], v[88:89], v[246:247] op_sel_hi:[1,0]
	v_pk_mul_f32 v[90:91], v[90:91], v[246:247] op_sel_hi:[1,0]
	v_cvt_pk_bf16_f32 v88, v88, v89
	v_cvt_pk_bf16_f32 v89, v90, v91
	global_store_dwordx2 v250, v[88:89], s[20:21] offset:160
	v_pk_mul_f32 v[92:93], v[92:93], v[246:247] op_sel_hi:[1,0]
	v_pk_mul_f32 v[94:95], v[94:95], v[246:247] op_sel_hi:[1,0]
	v_cvt_pk_bf16_f32 v92, v92, v93
	v_cvt_pk_bf16_f32 v93, v94, v95
	global_store_dwordx2 v250, v[92:93], s[20:21] offset:176
	v_pk_mul_f32 v[96:97], v[96:97], v[246:247] op_sel_hi:[1,0]
	v_pk_mul_f32 v[98:99], v[98:99], v[246:247] op_sel_hi:[1,0]
	v_cvt_pk_bf16_f32 v96, v96, v97
	v_cvt_pk_bf16_f32 v97, v98, v99
	global_store_dwordx2 v250, v[96:97], s[20:21] offset:192
	v_pk_mul_f32 v[100:101], v[100:101], v[246:247] op_sel_hi:[1,0]
	v_pk_mul_f32 v[102:103], v[102:103], v[246:247] op_sel_hi:[1,0]
	v_cvt_pk_bf16_f32 v100, v100, v101
	v_cvt_pk_bf16_f32 v101, v102, v103
	global_store_dwordx2 v250, v[100:101], s[20:21] offset:208
	v_pk_mul_f32 v[104:105], v[104:105], v[246:247] op_sel_hi:[1,0]
	v_pk_mul_f32 v[106:107], v[106:107], v[246:247] op_sel_hi:[1,0]
	v_cvt_pk_bf16_f32 v104, v104, v105
	v_cvt_pk_bf16_f32 v105, v106, v107
	global_store_dwordx2 v250, v[104:105], s[20:21] offset:224
	v_pk_mul_f32 v[108:109], v[108:109], v[246:247] op_sel_hi:[1,0]
	v_pk_mul_f32 v[110:111], v[110:111], v[246:247] op_sel_hi:[1,0]
	v_cvt_pk_bf16_f32 v108, v108, v109
	v_cvt_pk_bf16_f32 v109, v110, v111
	global_store_dwordx2 v250, v[108:109], s[20:21] offset:240
	v_mov_b32_e32 v133, 0
	s_waitcnt vmcnt(0)
	s_barrier
	s_and_saveexec_b64 s[0:1], s[24:25]
	s_cbranch_execz .LBB0_1145
	s_mov_b64 s[8:9], exec
	v_mbcnt_lo_u32_b32 v0, s8, 0
	v_mbcnt_hi_u32_b32 v0, s9, v0
	v_cmp_eq_u32_e32 vcc, 0, v0
	s_and_saveexec_b64 s[6:7], vcc
	s_cbranch_execz .LBB0_1144
	s_bcnt1_i32_b64 s8, s[8:9]
	v_mov_b32_e32 v1, s8
	global_atomic_add v1, v133, v1, s[42:43] sc0
	s_branch .LBB0_1144

; #define LAS __attribute__((address_space(3)))
; DI int otid() { int t = threadIdx.x; asm volatile("" : "+v"(t)); return t; }
; template <int DK>
; DI void dense_attn_item(LAS unsigned char* lds, const bf16_t* Qb, int ldq, const bf16_t* Kb, int ldk, const bf16_t* Kpe, const bf16_t* Vt, int nkeys, float sl2, bf16_t* Ob) {
;     const int tid = otid(), lane = tid & 63, wid = tid >> 6, r16 = lane & 15, q4 = lane >> 4;
;     constexpr int KS = DK / 32, KCH = DK / 8, KROW = DK * 2 + 16, KTILE = 64 * KROW, VROW = 144, VTILE = 128 * VROW, NKL = (64 * KCH) / 512;
;     bf16x8 qf[2][KS];
; #pragma unroll
;     for (int qg = 0; qg < 2; ++qg)
; #pragma unroll
;         for (int ks = 0; ks < KS; ++ks) qf[qg][ks] = *(const bf16x8*)(Qb + (size_t)(wid * 32 + qg * 16 + r16) * ldq + ks * 32 + q4 * 8);
;     f32x4 oacc[2][8];
; #pragma unroll
;     for (int qg = 0; qg < 2; ++qg)
; #pragma unroll
;         for (int d = 0; d < 8; ++d) oacc[qg][d] = (f32x4){0.f, 0.f, 0.f, 0.f};
;     float mrun[2] = {-1e30f, -1e30f}, lsum[2] = {0.f, 0.f};
;     u32x4 kst[NKL], vst[2];
;     const int ntiles = nkeys >> 6;
;     ...
;     DA_LOAD(0); DA_STORE(0);
;     __syncthreads();
; DI void dense192_item(unsigned char* ws, LAS unsigned char* lds, int b, int h, int q0, int nk) {
;     const size_t rowb = (size_t)b * RB, row0 = rowb + q0;
;     dense_attn_item<192>(lds, (const bf16_t*)(ws + WS_QM) + row0 * 960 + h * 192, 960, (const bf16_t*)(ws + WS_KM) + rowb * 640 + h * 128, 640, (const bf16_t*)(ws + WS_KPE) + rowb * 64,
;                          (const bf16_t*)(ws + WS_VTM) + ((size_t)b * 640 + h * 128) * RB, nk, 0.07216878364870322f * 1.4426950408889634f, (bf16_t*)(ws + WS_YMIX) + row0 * DM + 768 + h * 128);
.LBB0_2593:
	s_mul_hi_u32 s71, s0, 0x66666667
	s_lshr_b32 s71, s71, 4
	s_lshr_b32 s73, s0, 3
	s_mul_i32 s62, s71, 5
	s_sub_u32 s73, s73, s62
	s_and_b32 s62, s0, 7
	s_lshl_b32 s62, s62, 8
	s_mul_i32 s75, s71, 0x900
	s_add_u32 s74, s75, s62
	s_addk_i32 s74, 0x100
	s_mul_i32 s62, s74, 0x780
	s_mul_i32 s63, s73, 0x180
	s_add_u32 s62, s62, s63
	s_add_u32 s62, s62, 0x1a3a0000
	s_add_u32 s10, s50, s62
	s_addc_u32 s11, s51, 0
	s_mul_i32 s62, s75, 0x500
	s_lshl_b32 s63, s73, 8
	s_add_u32 s62, s62, s63
	s_add_u32 s62, s62, 0x1b480000
	s_add_u32 s4, s50, s62
	s_addc_u32 s5, s51, 0
	s_mul_i32 s62, s75, 0x480
	s_add_u32 s62, s62, s63
	s_sub_u32 s76, 0x167ff00, s62
	s_mul_i32 s62, s71, 0x280
	s_lshl_b32 s63, s73, 7
	s_add_u32 s62, s62, s63
	s_mul_i32 s62, s62, 0x1200
	s_add_u32 s62, s62, 0x1bfc0000
	s_add_u32 s8, s50, s62
	s_addc_u32 s9, s51, 0
	s_lshl_b32 s62, s74, 12
	s_lshl_b32 s63, s73, 8
	s_add_u32 s62, s62, s63
	s_add_u32 s62, s62, 0x1d9a0600
	s_add_u32 s20, s50, s62
	s_addc_u32 s21, s51, 0
	s_mov_b32 s22, 0x3dd53b94
	v_mov_b32_e32 v254, s22
	s_mov_b32 s29, 0x41000000
	v_and_b32_e32 v192, 31, v202
	v_bfe_u32 v193, v202, 5, 1
	v_lshrrev_b32_e32 v194, 6, v202
	v_lshl_add_u32 v195, v194, 5, v192
	v_mul_u32_u24_e32 v196, 0x780, v195
	v_lshl_add_u32 v250, v193, 4, v196
	global_load_dwordx4 v[0:3], v250, s[10:11] offset:0
	global_load_dwordx4 v[4:7], v250, s[10:11] offset:32
	global_load_dwordx4 v[8:11], v250, s[10:11] offset:64
	global_load_dwordx4 v[12:15], v250, s[10:11] offset:96
	global_load_dwordx4 v[16:19], v250, s[10:11] offset:128
	global_load_dwordx4 v[20:23], v250, s[10:11] offset:160
	global_load_dwordx4 v[24:27], v250, s[10:11] offset:192
	global_load_dwordx4 v[28:31], v250, s[10:11] offset:224
	global_load_dwordx4 v[32:35], v250, s[10:11] offset:256
	global_load_dwordx4 v[36:39], v250, s[10:11] offset:288
	global_load_dwordx4 v[40:43], v250, s[10:11] offset:320
	global_load_dwordx4 v[44:47], v250, s[10:11] offset:352
	s_mov_b32 s62, 0xaaaaaab
	v_mov_b32_e32 v197, v202
	v_mul_hi_u32 v198, v197, s62
	v_mul_u32_u24_e32 v195, 24, v198
	v_sub_u32_e32 v199, v197, v195
	v_mul_u32_u24_e32 v195, 0x190, v198
	v_lshl_add_u32 v230, v199, 4, v195
	v_cmp_gt_u32_e32 vcc, 16, v199
	v_mul_u32_u24_e32 v195, 0x500, v198
	v_lshlrev_b32_e32 v196, 7, v198
	v_add_u32_e32 v196, s76, v196
	s_nop 1
	v_cndmask_b32_e32 v195, v196, v195, vcc
	v_lshl_add_u32 v224, v199, 4, v195
	v_mov_b32_e32 v195, 0x2000
	v_mov_b32_e32 v196, 0x14000
	v_cndmask_b32_e32 v227, v195, v196, vcc
	v_add_u32_e32 v197, 0x200, v202
	v_mul_hi_u32 v198, v197, s62
	v_mul_u32_u24_e32 v195, 24, v198
	v_sub_u32_e32 v199, v197, v195
	v_mul_u32_u24_e32 v195, 0x190, v198
	v_lshl_add_u32 v231, v199, 4, v195
	v_cmp_gt_u32_e32 vcc, 16, v199
	v_mul_u32_u24_e32 v195, 0x500, v198
	v_lshlrev_b32_e32 v196, 7, v198
	v_add_u32_e32 v196, s76, v196
	s_nop 1
	v_cndmask_b32_e32 v195, v196, v195, vcc
	v_lshl_add_u32 v225, v199, 4, v195
	v_mov_b32_e32 v195, 0x2000
	v_mov_b32_e32 v196, 0x14000
	v_cndmask_b32_e32 v228, v195, v196, vcc
	v_add_u32_e32 v197, 0x400, v202
	v_mul_hi_u32 v198, v197, s62
	v_mul_u32_u24_e32 v195, 24, v198
	v_sub_u32_e32 v199, v197, v195
	v_mul_u32_u24_e32 v195, 0x190, v198
	v_lshl_add_u32 v232, v199, 4, v195
	v_cmp_gt_u32_e32 vcc, 16, v199
	v_mul_u32_u24_e32 v195, 0x500, v198
	v_lshlrev_b32_e32 v196, 7, v198
	v_add_u32_e32 v196, s76, v196
	s_nop 1
	v_cndmask_b32_e32 v195, v196, v195, vcc
	v_lshl_add_u32 v226, v199, 4, v195
	v_mov_b32_e32 v195, 0x2000
	v_mov_b32_e32 v196, 0x14000
	v_cndmask_b32_e32 v229, v195, v196, vcc
	v_mov_b32_e32 v197, v202
	v_lshrrev_b32_e32 v198, 3, v197
	v_and_b32_e32 v199, 7, v197
	v_mul_u32_u24_e32 v195, 0x1200, v198
	v_lshl_add_u32 v233, v199, 4, v195
	v_mul_u32_u24_e32 v195, 0x90, v198
	v_lshl_add_u32 v195, v199, 4, v195
	v_add_u32_e32 v235, 0x12c00, v195
	v_add_u32_e32 v197, 0x200, v202
	v_lshrrev_b32_e32 v198, 3, v197
	v_and_b32_e32 v199, 7, v197
	v_mul_u32_u24_e32 v195, 0x1200, v198
	v_lshl_add_u32 v234, v199, 4, v195
	v_mul_u32_u24_e32 v195, 0x90, v198
	v_lshl_add_u32 v195, v199, 4, v195
	v_add_u32_e32 v236, 0x12c00, v195
	v_mul_u32_u24_e32 v195, 0x190, v192
	v_lshl_add_u32 v237, v193, 4, v195
	v_mul_u32_u24_e32 v195, 0x90, v192
	v_lshl_add_u32 v195, v193, 3, v195
	v_add_u32_e32 v238, 0x12c00, v195
	global_load_dwordx4 v[204:207], v224, s[4:5]
	global_load_dwordx4 v[208:211], v225, s[4:5]
	global_load_dwordx4 v[212:215], v226, s[4:5]
	global_load_dwordx4 v[216:219], v233, s[8:9]
	global_load_dwordx4 v[220:223], v234, s[8:9]
	v_add_u32_e32 v224, v224, v227
	v_add_u32_e32 v225, v225, v228
	v_add_u32_e32 v226, v226, v229
	s_add_u32 s8, s8, 0x80
	s_addc_u32 s9, s9, 0
	v_mov_b32_e32 v48, 0
	v_mov_b32_e32 v49, 0
	v_mov_b32_e32 v50, 0
	v_mov_b32_e32 v51, 0
	v_mov_b32_e32 v52, 0
	v_mov_b32_e32 v53, 0
	v_mov_b32_e32 v54, 0
	v_mov_b32_e32 v55, 0
	v_mov_b32_e32 v56, 0
	v_mov_b32_e32 v57, 0
	v_mov_b32_e32 v58, 0
	v_mov_b32_e32 v59, 0
	v_mov_b32_e32 v60, 0
	v_mov_b32_e32 v61, 0
	v_mov_b32_e32 v62, 0
	v_mov_b32_e32 v63, 0
	v_mov_b32_e32 v64, 0
	v_mov_b32_e32 v65, 0
	v_mov_b32_e32 v66, 0
	v_mov_b32_e32 v67, 0
	v_mov_b32_e32 v68, 0
	v_mov_b32_e32 v69, 0
	v_mov_b32_e32 v70, 0
	v_mov_b32_e32 v71, 0
	v_mov_b32_e32 v72, 0
	v_mov_b32_e32 v73, 0
	v_mov_b32_e32 v74, 0
	v_mov_b32_e32 v75, 0
	v_mov_b32_e32 v76, 0
	v_mov_b32_e32 v77, 0
	v_mov_b32_e32 v78, 0
	v_mov_b32_e32 v79, 0
	v_mov_b32_e32 v80, 0
	v_mov_b32_e32 v81, 0
	v_mov_b32_e32 v82, 0
	v_mov_b32_e32 v83, 0
	v_mov_b32_e32 v84, 0
	v_mov_b32_e32 v85, 0
	v_mov_b32_e32 v86, 0
	v_mov_b32_e32 v87, 0
	v_mov_b32_e32 v88, 0
	v_mov_b32_e32 v89, 0
	v_mov_b32_e32 v90, 0
	v_mov_b32_e32 v91, 0
	v_mov_b32_e32 v92, 0
	v_mov_b32_e32 v93, 0
	v_mov_b32_e32 v94, 0
	v_mov_b32_e32 v95, 0
	v_mov_b32_e32 v96, 0
	v_mov_b32_e32 v97, 0
	v_mov_b32_e32 v98, 0
	v_mov_b32_e32 v99, 0
	v_mov_b32_e32 v100, 0
	v_mov_b32_e32 v101, 0
	v_mov_b32_e32 v102, 0
	v_mov_b32_e32 v103, 0
	v_mov_b32_e32 v104, 0
	v_mov_b32_e32 v105, 0
	v_mov_b32_e32 v106, 0
	v_mov_b32_e32 v107, 0
	v_mov_b32_e32 v108, 0
	v_mov_b32_e32 v109, 0
	v_mov_b32_e32 v110, 0
	v_mov_b32_e32 v111, 0
	v_mov_b32_e32 v242, 0xf149f2ca
	v_mov_b32_e32 v244, 0
	s_waitcnt vmcnt(0)
	v_lshl_add_u32 v195, v194, 5, v192
	v_lshlrev_b32_e32 v195, 12, v195
	v_lshl_add_u32 v250, v193, 3, v195
	ds_write_b128 v230, v[204:207]
	ds_write_b128 v231, v[208:211]
	ds_write_b128 v232, v[212:215]
	ds_write_b128 v235, v[216:219]
	ds_write_b128 v236, v[220:223]
	s_waitcnt lgkmcnt(0)
	global_load_dwordx4 v[204:207], v224, s[4:5]
	global_load_dwordx4 v[208:211], v225, s[4:5]
	global_load_dwordx4 v[212:215], v226, s[4:5]
	global_load_dwordx4 v[216:219], v233, s[8:9]
	global_load_dwordx4 v[220:223], v234, s[8:9]
	s_barrier
; #define LAS __attribute__((address_space(3)))
; template <int DK>
; DI void dense_attn_item(LAS unsigned char* lds, const bf16_t* Qb, int ldq, const bf16_t* Kb, int ldk, const bf16_t* Kpe, const bf16_t* Vt, int nkeys, float sl2, bf16_t* Ob) {
;     ...
;     DA_LOAD(0); DA_STORE(0);
;     __syncthreads();
;     for (int kt = 0; kt < ntiles; ++kt) {
;         const int cur = kt & 1;
;         if (kt + 1 < ntiles) DA_LOAD((kt + 1) * 64);
;         const LAS unsigned char* kb_ = lds + cur * KTILE; const LAS unsigned char* vb_ = lds + 2 * KTILE + cur * VTILE;
; #pragma unroll
;         for (int kc = 0; kc < 2; ++kc) {
;             f32x4 sacc[2][2];
; #pragma unroll
;             for (int kb = 0; kb < 2; ++kb) {
;                 sacc[0][kb] = (f32x4){0.f, 0.f, 0.f, 0.f}; sacc[1][kb] = (f32x4){0.f, 0.f, 0.f, 0.f};
; #pragma unroll
;                 for (int kh = 0; kh < KS / 2; ++kh) {
;                     const bf16x8 k0 = *(const LAS bf16x8*)(kb_ + ((2 * kc + kb) * 16 + r16) * KROW + (2 * kh) * 64 + q4 * 16);
;                     const bf16x8 k1 = *(const LAS bf16x8*)(kb_ + ((2 * kc + kb) * 16 + r16) * KROW + (2 * kh + 1) * 64 + q4 * 16);
;                     __builtin_amdgcn_s_setprio(1);
;                     sacc[0][kb] = MFMA16(k0, qf[0][2 * kh], sacc[0][kb]); sacc[1][kb] = MFMA16(k0, qf[1][2 * kh], sacc[1][kb]);
;                     sacc[0][kb] = MFMA16(k1, qf[0][2 * kh + 1], sacc[0][kb]); sacc[1][kb] = MFMA16(k1, qf[1][2 * kh + 1], sacc[1][kb]);
;                     __builtin_amdgcn_s_setprio(0);
;                 }
;             }
;             bf16x8 pb[2];
; #pragma unroll
;             for (int qg = 0; qg < 2; ++qg) {
;                 float mx = fmaxf(fmaxf(fmaxf(sacc[qg][0][0], sacc[qg][0][1]), fmaxf(sacc[qg][0][2], sacc[qg][0][3])), fmaxf(fmaxf(sacc[qg][1][0], sacc[qg][1][1]), fmaxf(sacc[qg][1][2], sacc[qg][1][3])));
;                 mx = fmaxf(mx, __shfl_xor(mx, 16)); mx = fmaxf(mx, __shfl_xor(mx, 32));
;                 const float mnew = fmaxf(mrun[qg], mx * sl2), alpha = fast_exp2(mrun[qg] - mnew);
;                 mrun[qg] = mnew;
;                 float ps = 0.f;
; #pragma unroll
;                 for (int kb = 0; kb < 2; ++kb)
; #pragma unroll
;                     for (int j = 0; j < 4; ++j) { const float pv = fast_exp2(sacc[qg][kb][j] * sl2 - mnew); sacc[qg][kb][j] = pv; ps += pv; }
	v_mov_b32_e32 v239, v237
	ds_read_b128 v[144:147], v239 offset:0
	ds_read_b128 v[148:151], v239 offset:32
	ds_read_b128 v[152:155], v239 offset:64
	ds_read_b128 v[156:159], v239 offset:96
	ds_read_b128 v[160:163], v239 offset:128
	ds_read_b128 v[164:167], v239 offset:160
	s_waitcnt lgkmcnt(5)
	v_mfma_f32_32x32x16_bf16 v[112:127], v[144:147], v[0:3], 0
	ds_read_b128 v[144:147], v239 offset:192
	s_waitcnt lgkmcnt(5)
	v_mfma_f32_32x32x16_bf16 v[112:127], v[148:151], v[4:7], v[112:127]
	ds_read_b128 v[148:151], v239 offset:224
	s_waitcnt lgkmcnt(5)
	v_mfma_f32_32x32x16_bf16 v[112:127], v[152:155], v[8:11], v[112:127]
	ds_read_b128 v[152:155], v239 offset:256
	s_waitcnt lgkmcnt(5)
	v_mfma_f32_32x32x16_bf16 v[112:127], v[156:159], v[12:15], v[112:127]
	ds_read_b128 v[156:159], v239 offset:288
	s_waitcnt lgkmcnt(5)
	v_mfma_f32_32x32x16_bf16 v[112:127], v[160:163], v[16:19], v[112:127]
	ds_read_b128 v[160:163], v239 offset:320
	s_waitcnt lgkmcnt(5)
	v_mfma_f32_32x32x16_bf16 v[112:127], v[164:167], v[20:23], v[112:127]
	ds_read_b128 v[164:167], v239 offset:352
	s_waitcnt lgkmcnt(5)
	v_mfma_f32_32x32x16_bf16 v[112:127], v[144:147], v[24:27], v[112:127]
	s_waitcnt lgkmcnt(4)
	v_mfma_f32_32x32x16_bf16 v[112:127], v[148:151], v[28:31], v[112:127]
	s_waitcnt lgkmcnt(3)
	v_mfma_f32_32x32x16_bf16 v[112:127], v[152:155], v[32:35], v[112:127]
	s_waitcnt lgkmcnt(2)
	v_mfma_f32_32x32x16_bf16 v[112:127], v[156:159], v[36:39], v[112:127]
	s_waitcnt lgkmcnt(1)
	v_mfma_f32_32x32x16_bf16 v[112:127], v[160:163], v[40:43], v[112:127]
	s_waitcnt lgkmcnt(0)
	v_mfma_f32_32x32x16_bf16 v[112:127], v[164:167], v[44:47], v[112:127]
	s_mov_b32 s23, 0
	s_mov_b32 s27, 0
dn1_top:
	s_add_u32 s57, s27, 1
	s_cmp_eq_u32 s57, 3
	s_cselect_b32 s57, 0, s57
	s_mul_i32 s36, s27, 0x6400
	s_mul_i32 s54, s27, 0x4800
	s_mul_i32 s37, s57, 0x6400
	s_mul_i32 s56, s57, 0x4800
	v_add_u32_e32 v239, s36, v237
	v_add_u32_e32 v240, s37, v237
	v_add_u32_e32 v241, s54, v238
	v_add_u32_e32 v196, s37, v230
	v_add_u32_e32 v197, s37, v231
	v_add_u32_e32 v198, s37, v232
	v_add_u32_e32 v199, s56, v235
	v_add_u32_e32 v200, s56, v236
	v_add_u32_e32 v224, v224, v227
	v_add_u32_e32 v225, v225, v228
	v_add_u32_e32 v226, v226, v229
	s_add_u32 s8, s8, 0x80
	s_addc_u32 s9, s9, 0
	s_waitcnt vmcnt(0)
	ds_write_b128 v196, v[204:207]
	ds_write_b128 v197, v[208:211]
	ds_write_b128 v198, v[212:215]
	ds_write_b128 v199, v[216:219]
	ds_write_b128 v200, v[220:223]
	ds_read_b128 v[144:147], v239 offset:12800
	ds_read_b128 v[148:151], v239 offset:12832
	ds_read_b128 v[152:155], v239 offset:12864
	ds_read_b128 v[156:159], v239 offset:12896
	ds_read_b128 v[160:163], v239 offset:12928
	ds_read_b128 v[164:167], v239 offset:12960
	v_max3_f32 v193, v112, v113, v114
	v_max3_f32 v192, v115, v116, v117
	v_max3_f32 v193, v193, v118, v119
	v_max3_f32 v192, v192, v120, v121
	v_max3_f32 v193, v193, v122, v123
	v_max3_f32 v192, v192, v124, v125
	v_max3_f32 v193, v193, v126, v127
	v_max_f32_e32 v193, v193, v192
	v_mov_b32_e32 v192, v193
	s_nop 1
	s_waitcnt lgkmcnt(5)
	global_load_dwordx4 v[204:207], v224, s[4:5]
	global_load_dwordx4 v[208:211], v225, s[4:5]
	global_load_dwordx4 v[212:215], v226, s[4:5]
	global_load_dwordx4 v[216:219], v233, s[8:9]
	global_load_dwordx4 v[220:223], v234, s[8:9]
	v_mfma_f32_32x32x16_bf16 v[128:143], v[144:147], v[0:3], 0
	v_permlane32_swap_b32_e32 v193, v192
	v_max_f32_e32 v193, v193, v192
	v_mul_f32_e32 v193, s22, v193
	v_max_f32_e32 v192, v242, v193
	v_sub_f32_e32 v193, v192, v242
	ds_read_b128 v[144:147], v239 offset:12992
	s_waitcnt lgkmcnt(5)
	v_mfma_f32_32x32x16_bf16 v[128:143], v[148:151], v[4:7], v[128:143]
	v_cmp_gt_f32_e64 s[68:69], v193, s29
	s_cmp_lg_u64 s[68:69], 0
	s_cselect_b64 s[68:69], -1, 0
	v_cndmask_b32_e64 v192, v242, v192, s[68:69]
	v_sub_f32_e32 v193, v242, v192
	ds_read_b128 v[148:151], v239 offset:13024
	s_waitcnt lgkmcnt(5)
	v_mfma_f32_32x32x16_bf16 v[128:143], v[152:155], v[8:11], v[128:143]
	v_exp_f32_e32 v246, v193
	v_mov_b32_e32 v242, v192
	v_pk_fma_f32 v[112:113], v[112:113], v[254:255], v[192:193] op_sel_hi:[1,0,0] neg_lo:[0,0,1] neg_hi:[0,0,1]
	v_pk_fma_f32 v[114:115], v[114:115], v[254:255], v[192:193] op_sel_hi:[1,0,0] neg_lo:[0,0,1] neg_hi:[0,0,1]
	v_pk_fma_f32 v[116:117], v[116:117], v[254:255], v[192:193] op_sel_hi:[1,0,0] neg_lo:[0,0,1] neg_hi:[0,0,1]
	ds_read_b128 v[152:155], v239 offset:13056
	s_waitcnt lgkmcnt(5)
	v_mfma_f32_32x32x16_bf16 v[128:143], v[156:159], v[12:15], v[128:143]
	v_pk_fma_f32 v[118:119], v[118:119], v[254:255], v[192:193] op_sel_hi:[1,0,0] neg_lo:[0,0,1] neg_hi:[0,0,1]
	v_pk_fma_f32 v[120:121], v[120:121], v[254:255], v[192:193] op_sel_hi:[1,0,0] neg_lo:[0,0,1] neg_hi:[0,0,1]
	v_pk_fma_f32 v[122:123], v[122:123], v[254:255], v[192:193] op_sel_hi:[1,0,0] neg_lo:[0,0,1] neg_hi:[0,0,1]
	v_pk_fma_f32 v[124:125], v[124:125], v[254:255], v[192:193] op_sel_hi:[1,0,0] neg_lo:[0,0,1] neg_hi:[0,0,1]
	v_pk_fma_f32 v[126:127], v[126:127], v[254:255], v[192:193] op_sel_hi:[1,0,0] neg_lo:[0,0,1] neg_hi:[0,0,1]
	ds_read_b128 v[156:159], v239 offset:13088
	s_waitcnt lgkmcnt(5)
	v_mfma_f32_32x32x16_bf16 v[128:143], v[160:163], v[16:19], v[128:143]
	v_exp_f32_e32 v112, v112
	v_exp_f32_e32 v113, v113
	v_exp_f32_e32 v114, v114
	v_exp_f32_e32 v115, v115
	v_exp_f32_e32 v116, v116
	ds_read_b128 v[160:163], v239 offset:13120
	s_waitcnt lgkmcnt(5)
	v_mfma_f32_32x32x16_bf16 v[128:143], v[164:167], v[20:23], v[128:143]
	v_exp_f32_e32 v117, v117
	v_exp_f32_e32 v118, v118
	v_exp_f32_e32 v119, v119
	v_exp_f32_e32 v120, v120
	v_exp_f32_e32 v121, v121
	ds_read_b128 v[164:167], v239 offset:13152
	s_waitcnt lgkmcnt(5)
; template <int DK>
; DI void dense_attn_item(LAS unsigned char* lds, const bf16_t* Qb, int ldq, const bf16_t* Kb, int ldk, const bf16_t* Kpe, const bf16_t* Vt, int nkeys, float sl2, bf16_t* Ob) {
;     ...
;             for (int kb = 0; kb < 2; ++kb) {
;                 sacc[0][kb] = (f32x4){0.f, 0.f, 0.f, 0.f}; sacc[1][kb] = (f32x4){0.f, 0.f, 0.f, 0.f};
; #pragma unroll
;                 for (int kh = 0; kh < KS / 2; ++kh) {
;                     const bf16x8 k0 = *(const LAS bf16x8*)(kb_ + ((2 * kc + kb) * 16 + r16) * KROW + (2 * kh) * 64 + q4 * 16);
;                     const bf16x8 k1 = *(const LAS bf16x8*)(kb_ + ((2 * kc + kb) * 16 + r16) * KROW + (2 * kh + 1) * 64 + q4 * 16);
;                     __builtin_amdgcn_s_setprio(1);
;                     sacc[0][kb] = MFMA16(k0, qf[0][2 * kh], sacc[0][kb]); sacc[1][kb] = MFMA16(k0, qf[1][2 * kh], sacc[1][kb]);
;                     sacc[0][kb] = MFMA16(k1, qf[0][2 * kh + 1], sacc[0][kb]); sacc[1][kb] = MFMA16(k1, qf[1][2 * kh + 1], sacc[1][kb]);
;                     __builtin_amdgcn_s_setprio(0);
;                 }
;             }
;             bf16x8 pb[2];
; #pragma unroll
;             for (int qg = 0; qg < 2; ++qg) {
;                 float mx = fmaxf(fmaxf(fmaxf(sacc[qg][0][0], sacc[qg][0][1]), fmaxf(sacc[qg][0][2], sacc[qg][0][3])), fmaxf(fmaxf(sacc[qg][1][0], sacc[qg][1][1]), fmaxf(sacc[qg][1][2], sacc[qg][1][3])));
;                 mx = fmaxf(mx, __shfl_xor(mx, 16)); mx = fmaxf(mx, __shfl_xor(mx, 32));
;                 const float mnew = fmaxf(mrun[qg], mx * sl2), alpha = fast_exp2(mrun[qg] - mnew);
;                 mrun[qg] = mnew;
;                 float ps = 0.f;
; #pragma unroll
;                 for (int kb = 0; kb < 2; ++kb)
; #pragma unroll
;                     for (int j = 0; j < 4; ++j) { const float pv = fast_exp2(sacc[qg][kb][j] * sl2 - mnew); sacc[qg][kb][j] = pv; ps += pv; }
;                 lsum[qg] = lsum[qg] * alpha + ps;
; #pragma unroll
;                 for (int d = 0; d < 8; ++d) oacc[qg][d] *= alpha;
;                 u32x4 w; w.x = cvt_pk_bf16(sacc[qg][0][0], sacc[qg][0][1]); w.y = cvt_pk_bf16(sacc[qg][0][2], sacc[qg][0][3]);
;                 w.z = cvt_pk_bf16(sacc[qg][1][0], sacc[qg][1][1]); w.w = cvt_pk_bf16(sacc[qg][1][2], sacc[qg][1][3]);
;                 pb[qg] = __builtin_bit_cast(bf16x8, w);
;             }
; #pragma unroll
	v_mfma_f32_32x32x16_bf16 v[128:143], v[144:147], v[24:27], v[128:143]
	v_exp_f32_e32 v122, v122
	v_exp_f32_e32 v123, v123
	v_exp_f32_e32 v124, v124
	v_exp_f32_e32 v125, v125
	v_exp_f32_e32 v126, v126
	ds_read_b64 v[168:169], v241 offset:0
	ds_read_b64 v[170:171], v241 offset:16
	s_waitcnt lgkmcnt(6)
	v_mfma_f32_32x32x16_bf16 v[128:143], v[148:151], v[28:31], v[128:143]
	v_exp_f32_e32 v127, v127
	v_pk_add_f32 v[196:197], v[112:113], v[114:115]
	v_pk_add_f32 v[198:199], v[116:117], v[118:119]
	v_pk_add_f32 v[196:197], v[196:197], v[120:121]
	v_pk_add_f32 v[198:199], v[198:199], v[122:123]
	ds_read_b64 v[172:173], v241 offset:32
	ds_read_b64 v[174:175], v241 offset:48
	s_waitcnt lgkmcnt(7)
	v_mfma_f32_32x32x16_bf16 v[128:143], v[152:155], v[32:35], v[128:143]
	v_pk_add_f32 v[196:197], v[196:197], v[124:125]
	v_pk_add_f32 v[198:199], v[198:199], v[126:127]
	v_pk_add_f32 v[196:197], v[196:197], v[198:199]
	v_add_f32_e32 v193, v196, v197
	v_fma_f32 v244, v244, v246, v193
	ds_read_b64 v[176:177], v241 offset:4608
	ds_read_b64 v[178:179], v241 offset:4624
	s_waitcnt lgkmcnt(8)
	v_mfma_f32_32x32x16_bf16 v[128:143], v[156:159], v[36:39], v[128:143]
	v_cvt_pk_bf16_f32 v184, v112, v113
	v_cvt_pk_bf16_f32 v185, v114, v115
	v_cvt_pk_bf16_f32 v186, v116, v117
	v_cvt_pk_bf16_f32 v187, v118, v119
	v_cvt_pk_bf16_f32 v188, v120, v121
	ds_read_b64 v[180:181], v241 offset:4640
	ds_read_b64 v[182:183], v241 offset:4656
	s_waitcnt lgkmcnt(9)
	v_mfma_f32_32x32x16_bf16 v[128:143], v[160:163], v[40:43], v[128:143]
	v_cvt_pk_bf16_f32 v189, v122, v123
	v_cvt_pk_bf16_f32 v190, v124, v125
	v_cvt_pk_bf16_f32 v191, v126, v127
	s_waitcnt lgkmcnt(8)
	v_mfma_f32_32x32x16_bf16 v[128:143], v[164:167], v[44:47], v[128:143]
	s_mov_b64 vcc, s[68:69]
	s_cbranch_vccz dn1_nr1
	v_pk_mul_f32 v[48:49], v[48:49], v[246:247] op_sel_hi:[1,0]
	v_pk_mul_f32 v[50:51], v[50:51], v[246:247] op_sel_hi:[1,0]
	v_pk_mul_f32 v[52:53], v[52:53], v[246:247] op_sel_hi:[1,0]
	v_pk_mul_f32 v[54:55], v[54:55], v[246:247] op_sel_hi:[1,0]
	v_pk_mul_f32 v[56:57], v[56:57], v[246:247] op_sel_hi:[1,0]
	v_pk_mul_f32 v[58:59], v[58:59], v[246:247] op_sel_hi:[1,0]
	v_pk_mul_f32 v[60:61], v[60:61], v[246:247] op_sel_hi:[1,0]
	v_pk_mul_f32 v[62:63], v[62:63], v[246:247] op_sel_hi:[1,0]
	s_waitcnt lgkmcnt(6)
	v_mfma_f32_32x32x16_bf16 v[48:63], v[168:171], v[184:187], v[48:63]
	v_pk_mul_f32 v[64:65], v[64:65], v[246:247] op_sel_hi:[1,0]
	v_pk_mul_f32 v[66:67], v[66:67], v[246:247] op_sel_hi:[1,0]
	v_pk_mul_f32 v[68:69], v[68:69], v[246:247] op_sel_hi:[1,0]
	v_pk_mul_f32 v[70:71], v[70:71], v[246:247] op_sel_hi:[1,0]
	ds_read_b64 v[168:169], v241 offset:9216
	ds_read_b64 v[170:171], v241 offset:9232
	s_waitcnt lgkmcnt(6)
	v_mfma_f32_32x32x16_bf16 v[48:63], v[172:175], v[188:191], v[48:63]
	v_pk_mul_f32 v[72:73], v[72:73], v[246:247] op_sel_hi:[1,0]
	v_pk_mul_f32 v[74:75], v[74:75], v[246:247] op_sel_hi:[1,0]
	v_pk_mul_f32 v[76:77], v[76:77], v[246:247] op_sel_hi:[1,0]
	v_pk_mul_f32 v[78:79], v[78:79], v[246:247] op_sel_hi:[1,0]
	ds_read_b64 v[172:173], v241 offset:9248
	ds_read_b64 v[174:175], v241 offset:9264
	s_waitcnt lgkmcnt(6)
	v_mfma_f32_32x32x16_bf16 v[64:79], v[176:179], v[184:187], v[64:79]
	v_pk_mul_f32 v[80:81], v[80:81], v[246:247] op_sel_hi:[1,0]
	v_pk_mul_f32 v[82:83], v[82:83], v[246:247] op_sel_hi:[1,0]
	v_pk_mul_f32 v[84:85], v[84:85], v[246:247] op_sel_hi:[1,0]
	v_pk_mul_f32 v[86:87], v[86:87], v[246:247] op_sel_hi:[1,0]
	ds_read_b64 v[176:177], v241 offset:13824
	ds_read_b64 v[178:179], v241 offset:13840
	s_waitcnt lgkmcnt(6)
	v_mfma_f32_32x32x16_bf16 v[64:79], v[180:183], v[188:191], v[64:79]
	v_pk_mul_f32 v[88:89], v[88:89], v[246:247] op_sel_hi:[1,0]
	v_pk_mul_f32 v[90:91], v[90:91], v[246:247] op_sel_hi:[1,0]
	v_pk_mul_f32 v[92:93], v[92:93], v[246:247] op_sel_hi:[1,0]
	v_pk_mul_f32 v[94:95], v[94:95], v[246:247] op_sel_hi:[1,0]
	ds_read_b64 v[180:181], v241 offset:13856
	ds_read_b64 v[182:183], v241 offset:13872
	s_waitcnt lgkmcnt(6)
	v_mfma_f32_32x32x16_bf16 v[80:95], v[168:171], v[184:187], v[80:95]
	v_pk_mul_f32 v[96:97], v[96:97], v[246:247] op_sel_hi:[1,0]
	v_pk_mul_f32 v[98:99], v[98:99], v[246:247] op_sel_hi:[1,0]
	v_pk_mul_f32 v[100:101], v[100:101], v[246:247] op_sel_hi:[1,0]
	v_pk_mul_f32 v[102:103], v[102:103], v[246:247] op_sel_hi:[1,0]
	s_nop 1
	s_waitcnt lgkmcnt(4)
	v_mfma_f32_32x32x16_bf16 v[80:95], v[172:175], v[188:191], v[80:95]
	v_pk_mul_f32 v[104:105], v[104:105], v[246:247] op_sel_hi:[1,0]
	v_pk_mul_f32 v[106:107], v[106:107], v[246:247] op_sel_hi:[1,0]
	v_pk_mul_f32 v[108:109], v[108:109], v[246:247] op_sel_hi:[1,0]
	v_pk_mul_f32 v[110:111], v[110:111], v[246:247] op_sel_hi:[1,0]
	s_nop 1
	s_waitcnt lgkmcnt(2)
	v_mfma_f32_32x32x16_bf16 v[96:111], v[176:179], v[184:187], v[96:111]
	s_waitcnt lgkmcnt(0)
	v_mfma_f32_32x32x16_bf16 v[96:111], v[180:183], v[188:191], v[96:111]
	s_branch dn1_jn1
dn1_nr1:
	s_nop 1
	s_waitcnt lgkmcnt(6)
	v_mfma_f32_32x32x16_bf16 v[48:63], v[168:171], v[184:187], v[48:63]
	ds_read_b64 v[168:169], v241 offset:9216
	ds_read_b64 v[170:171], v241 offset:9232
	s_waitcnt lgkmcnt(6)
	v_mfma_f32_32x32x16_bf16 v[48:63], v[172:175], v[188:191], v[48:63]
	ds_read_b64 v[172:173], v241 offset:9248
	ds_read_b64 v[174:175], v241 offset:9264
	s_waitcnt lgkmcnt(6)
	v_mfma_f32_32x32x16_bf16 v[64:79], v[176:179], v[184:187], v[64:79]
	ds_read_b64 v[176:177], v241 offset:13824
	ds_read_b64 v[178:179], v241 offset:13840
	s_waitcnt lgkmcnt(6)
	v_mfma_f32_32x32x16_bf16 v[64:79], v[180:183], v[188:191], v[64:79]
	ds_read_b64 v[180:181], v241 offset:13856
	ds_read_b64 v[182:183], v241 offset:13872
	s_waitcnt lgkmcnt(6)
	v_mfma_f32_32x32x16_bf16 v[80:95], v[168:171], v[184:187], v[80:95]
	s_waitcnt lgkmcnt(4)
	v_mfma_f32_32x32x16_bf16 v[80:95], v[172:175], v[188:191], v[80:95]
	s_waitcnt lgkmcnt(2)
	v_mfma_f32_32x32x16_bf16 v[96:111], v[176:179], v[184:187], v[96:111]
	s_waitcnt lgkmcnt(0)
	v_mfma_f32_32x32x16_bf16 v[96:111], v[180:183], v[188:191], v[96:111]
; template <int DK>
; DI void dense_attn_item(LAS unsigned char* lds, const bf16_t* Qb, int ldq, const bf16_t* Kb, int ldk, const bf16_t* Kpe, const bf16_t* Vt, int nkeys, float sl2, bf16_t* Ob) {
;     ...
;         for (int kc = 0; kc < 2; ++kc) {
;             f32x4 sacc[2][2];
; #pragma unroll
;             for (int kb = 0; kb < 2; ++kb) {
;                 sacc[0][kb] = (f32x4){0.f, 0.f, 0.f, 0.f}; sacc[1][kb] = (f32x4){0.f, 0.f, 0.f, 0.f};
; #pragma unroll
;                 for (int kh = 0; kh < KS / 2; ++kh) {
;                     const bf16x8 k0 = *(const LAS bf16x8*)(kb_ + ((2 * kc + kb) * 16 + r16) * KROW + (2 * kh) * 64 + q4 * 16);
;                     const bf16x8 k1 = *(const LAS bf16x8*)(kb_ + ((2 * kc + kb) * 16 + r16) * KROW + (2 * kh + 1) * 64 + q4 * 16);
;                     __builtin_amdgcn_s_setprio(1);
;                     sacc[0][kb] = MFMA16(k0, qf[0][2 * kh], sacc[0][kb]); sacc[1][kb] = MFMA16(k0, qf[1][2 * kh], sacc[1][kb]);
;                     sacc[0][kb] = MFMA16(k1, qf[0][2 * kh + 1], sacc[0][kb]); sacc[1][kb] = MFMA16(k1, qf[1][2 * kh + 1], sacc[1][kb]);
;                     __builtin_amdgcn_s_setprio(0);
;                 }
;             }
;             bf16x8 pb[2];
; #pragma unroll
;             for (int qg = 0; qg < 2; ++qg) {
;                 float mx = fmaxf(fmaxf(fmaxf(sacc[qg][0][0], sacc[qg][0][1]), fmaxf(sacc[qg][0][2], sacc[qg][0][3])), fmaxf(fmaxf(sacc[qg][1][0], sacc[qg][1][1]), fmaxf(sacc[qg][1][2], sacc[qg][1][3])));
;                 mx = fmaxf(mx, __shfl_xor(mx, 16)); mx = fmaxf(mx, __shfl_xor(mx, 32));
;                 const float mnew = fmaxf(mrun[qg], mx * sl2), alpha = fast_exp2(mrun[qg] - mnew);
;                 mrun[qg] = mnew;
;                 float ps = 0.f;
; #pragma unroll
;                 for (int kb = 0; kb < 2; ++kb)
; #pragma unroll
;                     for (int j = 0; j < 4; ++j) { const float pv = fast_exp2(sacc[qg][kb][j] * sl2 - mnew); sacc[qg][kb][j] = pv; ps += pv; }
;                 lsum[qg] = lsum[qg] * alpha + ps;
; #pragma unroll
;                 for (int d = 0; d < 8; ++d) oacc[qg][d] *= alpha;
;                 u32x4 w; w.x = cvt_pk_bf16(sacc[qg][0][0], sacc[qg][0][1]); w.y = cvt_pk_bf16(sacc[qg][0][2], sacc[qg][0][3]);
;                 w.z = cvt_pk_bf16(sacc[qg][1][0], sacc[qg][1][1]); w.w = cvt_pk_bf16(sacc[qg][1][2], sacc[qg][1][3]);
dn1_jn1:
	s_waitcnt lgkmcnt(0)
	s_barrier
	ds_read_b128 v[144:147], v240 offset:0
	ds_read_b128 v[148:151], v240 offset:32
	ds_read_b128 v[152:155], v240 offset:64
	ds_read_b128 v[156:159], v240 offset:96
	ds_read_b128 v[160:163], v240 offset:128
	ds_read_b128 v[164:167], v240 offset:160
	v_max3_f32 v193, v128, v129, v130
	v_max3_f32 v192, v131, v132, v133
	v_max3_f32 v193, v193, v134, v135
	v_max3_f32 v192, v192, v136, v137
	v_max3_f32 v193, v193, v138, v139
	v_max3_f32 v192, v192, v140, v141
	v_max3_f32 v193, v193, v142, v143
	v_max_f32_e32 v193, v193, v192
	v_mov_b32_e32 v192, v193
	s_nop 1
	s_waitcnt lgkmcnt(5)
	v_mfma_f32_32x32x16_bf16 v[112:127], v[144:147], v[0:3], 0
	v_permlane32_swap_b32_e32 v193, v192
	v_max_f32_e32 v193, v193, v192
	v_mul_f32_e32 v193, s22, v193
	v_max_f32_e32 v192, v242, v193
	v_sub_f32_e32 v193, v192, v242
	ds_read_b128 v[144:147], v240 offset:192
	s_waitcnt lgkmcnt(5)
	v_mfma_f32_32x32x16_bf16 v[112:127], v[148:151], v[4:7], v[112:127]
	v_cmp_gt_f32_e64 s[68:69], v193, s29
	s_cmp_lg_u64 s[68:69], 0
	s_cselect_b64 s[68:69], -1, 0
	v_cndmask_b32_e64 v192, v242, v192, s[68:69]
	v_sub_f32_e32 v193, v242, v192
	ds_read_b128 v[148:151], v240 offset:224
	s_waitcnt lgkmcnt(5)
	v_mfma_f32_32x32x16_bf16 v[112:127], v[152:155], v[8:11], v[112:127]
	v_exp_f32_e32 v246, v193
	v_mov_b32_e32 v242, v192
	v_pk_fma_f32 v[128:129], v[128:129], v[254:255], v[192:193] op_sel_hi:[1,0,0] neg_lo:[0,0,1] neg_hi:[0,0,1]
	v_pk_fma_f32 v[130:131], v[130:131], v[254:255], v[192:193] op_sel_hi:[1,0,0] neg_lo:[0,0,1] neg_hi:[0,0,1]
	v_pk_fma_f32 v[132:133], v[132:133], v[254:255], v[192:193] op_sel_hi:[1,0,0] neg_lo:[0,0,1] neg_hi:[0,0,1]
	ds_read_b128 v[152:155], v240 offset:256
	s_waitcnt lgkmcnt(5)
	v_mfma_f32_32x32x16_bf16 v[112:127], v[156:159], v[12:15], v[112:127]
	v_pk_fma_f32 v[134:135], v[134:135], v[254:255], v[192:193] op_sel_hi:[1,0,0] neg_lo:[0,0,1] neg_hi:[0,0,1]
	v_pk_fma_f32 v[136:137], v[136:137], v[254:255], v[192:193] op_sel_hi:[1,0,0] neg_lo:[0,0,1] neg_hi:[0,0,1]
	v_pk_fma_f32 v[138:139], v[138:139], v[254:255], v[192:193] op_sel_hi:[1,0,0] neg_lo:[0,0,1] neg_hi:[0,0,1]
	v_pk_fma_f32 v[140:141], v[140:141], v[254:255], v[192:193] op_sel_hi:[1,0,0] neg_lo:[0,0,1] neg_hi:[0,0,1]
	v_pk_fma_f32 v[142:143], v[142:143], v[254:255], v[192:193] op_sel_hi:[1,0,0] neg_lo:[0,0,1] neg_hi:[0,0,1]
	ds_read_b128 v[156:159], v240 offset:288
	s_waitcnt lgkmcnt(5)
	v_mfma_f32_32x32x16_bf16 v[112:127], v[160:163], v[16:19], v[112:127]
	v_exp_f32_e32 v128, v128
	v_exp_f32_e32 v129, v129
	v_exp_f32_e32 v130, v130
	v_exp_f32_e32 v131, v131
	v_exp_f32_e32 v132, v132
	ds_read_b128 v[160:163], v240 offset:320
	s_waitcnt lgkmcnt(5)
	v_mfma_f32_32x32x16_bf16 v[112:127], v[164:167], v[20:23], v[112:127]
	v_exp_f32_e32 v133, v133
	v_exp_f32_e32 v134, v134
	v_exp_f32_e32 v135, v135
	v_exp_f32_e32 v136, v136
	v_exp_f32_e32 v137, v137
	ds_read_b128 v[164:167], v240 offset:352
	s_waitcnt lgkmcnt(5)
	v_mfma_f32_32x32x16_bf16 v[112:127], v[144:147], v[24:27], v[112:127]
	v_exp_f32_e32 v138, v138
	v_exp_f32_e32 v139, v139
	v_exp_f32_e32 v140, v140
	v_exp_f32_e32 v141, v141
	v_exp_f32_e32 v142, v142
	ds_read_b64 v[168:169], v241 offset:64
	ds_read_b64 v[170:171], v241 offset:80
	s_waitcnt lgkmcnt(6)
	v_mfma_f32_32x32x16_bf16 v[112:127], v[148:151], v[28:31], v[112:127]
	v_exp_f32_e32 v143, v143
	v_pk_add_f32 v[196:197], v[128:129], v[130:131]
	v_pk_add_f32 v[198:199], v[132:133], v[134:135]
	v_pk_add_f32 v[196:197], v[196:197], v[136:137]
	v_pk_add_f32 v[198:199], v[198:199], v[138:139]
	ds_read_b64 v[172:173], v241 offset:96
	ds_read_b64 v[174:175], v241 offset:112
	s_waitcnt lgkmcnt(7)
	v_mfma_f32_32x32x16_bf16 v[112:127], v[152:155], v[32:35], v[112:127]
	v_pk_add_f32 v[196:197], v[196:197], v[140:141]
	v_pk_add_f32 v[198:199], v[198:199], v[142:143]
	v_pk_add_f32 v[196:197], v[196:197], v[198:199]
	v_add_f32_e32 v193, v196, v197
	v_fma_f32 v244, v244, v246, v193
	ds_read_b64 v[176:177], v241 offset:4672
	ds_read_b64 v[178:179], v241 offset:4688
	s_waitcnt lgkmcnt(8)
	v_mfma_f32_32x32x16_bf16 v[112:127], v[156:159], v[36:39], v[112:127]
	v_cvt_pk_bf16_f32 v184, v128, v129
	v_cvt_pk_bf16_f32 v185, v130, v131
	v_cvt_pk_bf16_f32 v186, v132, v133
	v_cvt_pk_bf16_f32 v187, v134, v135
	v_cvt_pk_bf16_f32 v188, v136, v137
	ds_read_b64 v[180:181], v241 offset:4704
	ds_read_b64 v[182:183], v241 offset:4720
	s_waitcnt lgkmcnt(9)
	v_mfma_f32_32x32x16_bf16 v[112:127], v[160:163], v[40:43], v[112:127]
	v_cvt_pk_bf16_f32 v189, v138, v139
	v_cvt_pk_bf16_f32 v190, v140, v141
	v_cvt_pk_bf16_f32 v191, v142, v143
	s_waitcnt lgkmcnt(8)
	v_mfma_f32_32x32x16_bf16 v[112:127], v[164:167], v[44:47], v[112:127]
	s_mov_b64 vcc, s[68:69]
	s_cbranch_vccz dn1_nr2
; #define LAS __attribute__((address_space(3)))
; DI unsigned cvt_pk_bf16(float lo, float hi) { unsigned r; asm volatile("v_cvt_pk_bf16_f32 %0, %1, %2" : "=v"(r) : "v"(lo), "v"(hi)); return r; }
; #define MFMA16(a, b, c) __builtin_amdgcn_mfma_f32_16x16x32_bf16((a), (b), (c), 0, 0, 0)
; template <int DK>
; DI void dense_attn_item(LAS unsigned char* lds, const bf16_t* Qb, int ldq, const bf16_t* Kb, int ldk, const bf16_t* Kpe, const bf16_t* Vt, int nkeys, float sl2, bf16_t* Ob) {
;     ...
;                 for (int d = 0; d < 8; ++d) oacc[qg][d] *= alpha;
;                 u32x4 w; w.x = cvt_pk_bf16(sacc[qg][0][0], sacc[qg][0][1]); w.y = cvt_pk_bf16(sacc[qg][0][2], sacc[qg][0][3]);
;                 w.z = cvt_pk_bf16(sacc[qg][1][0], sacc[qg][1][1]); w.w = cvt_pk_bf16(sacc[qg][1][2], sacc[qg][1][3]);
;                 pb[qg] = __builtin_bit_cast(bf16x8, w);
;             }
; #pragma unroll
;             for (int dh = 0; dh < 4; ++dh) {
;                 bf16x8 vfr[2];
; #pragma unroll
;                 for (int d4 = 0; d4 < 2; ++d4) {
;                     const int d = dh * 2 + d4;
;                     const u32x2 lo = *(const LAS u32x2*)(vb_ + (d * 16 + r16) * VROW + (kc * 32 + q4 * 4) * 2);
;                     const u32x2 hi = *(const LAS u32x2*)(vb_ + (d * 16 + r16) * VROW + (kc * 32 + 16 + q4 * 4) * 2);
;                     u32x4 w; w.x = lo.x; w.y = lo.y; w.z = hi.x; w.w = hi.y;
;                     vfr[d4] = __builtin_bit_cast(bf16x8, w);
;                 }
;                 __builtin_amdgcn_s_setprio(1);
; #pragma unroll
;                 for (int d4 = 0; d4 < 2; ++d4) { const int d = dh * 2 + d4; oacc[0][d] = MFMA16(vfr[d4], pb[0], oacc[0][d]); oacc[1][d] = MFMA16(vfr[d4], pb[1], oacc[1][d]); }
;                 __builtin_amdgcn_s_setprio(0);
;             }
	v_pk_mul_f32 v[48:49], v[48:49], v[246:247] op_sel_hi:[1,0]
	v_pk_mul_f32 v[50:51], v[50:51], v[246:247] op_sel_hi:[1,0]
	v_pk_mul_f32 v[52:53], v[52:53], v[246:247] op_sel_hi:[1,0]
	v_pk_mul_f32 v[54:55], v[54:55], v[246:247] op_sel_hi:[1,0]
	v_pk_mul_f32 v[56:57], v[56:57], v[246:247] op_sel_hi:[1,0]
	v_pk_mul_f32 v[58:59], v[58:59], v[246:247] op_sel_hi:[1,0]
	v_pk_mul_f32 v[60:61], v[60:61], v[246:247] op_sel_hi:[1,0]
	v_pk_mul_f32 v[62:63], v[62:63], v[246:247] op_sel_hi:[1,0]
	s_waitcnt lgkmcnt(6)
	v_mfma_f32_32x32x16_bf16 v[48:63], v[168:171], v[184:187], v[48:63]
	v_pk_mul_f32 v[64:65], v[64:65], v[246:247] op_sel_hi:[1,0]
	v_pk_mul_f32 v[66:67], v[66:67], v[246:247] op_sel_hi:[1,0]
	v_pk_mul_f32 v[68:69], v[68:69], v[246:247] op_sel_hi:[1,0]
	v_pk_mul_f32 v[70:71], v[70:71], v[246:247] op_sel_hi:[1,0]
	ds_read_b64 v[168:169], v241 offset:9280
	ds_read_b64 v[170:171], v241 offset:9296
	s_waitcnt lgkmcnt(6)
	v_mfma_f32_32x32x16_bf16 v[48:63], v[172:175], v[188:191], v[48:63]
	v_pk_mul_f32 v[72:73], v[72:73], v[246:247] op_sel_hi:[1,0]
	v_pk_mul_f32 v[74:75], v[74:75], v[246:247] op_sel_hi:[1,0]
	v_pk_mul_f32 v[76:77], v[76:77], v[246:247] op_sel_hi:[1,0]
	v_pk_mul_f32 v[78:79], v[78:79], v[246:247] op_sel_hi:[1,0]
	ds_read_b64 v[172:173], v241 offset:9312
	ds_read_b64 v[174:175], v241 offset:9328
	s_waitcnt lgkmcnt(6)
	v_mfma_f32_32x32x16_bf16 v[64:79], v[176:179], v[184:187], v[64:79]
	v_pk_mul_f32 v[80:81], v[80:81], v[246:247] op_sel_hi:[1,0]
	v_pk_mul_f32 v[82:83], v[82:83], v[246:247] op_sel_hi:[1,0]
	v_pk_mul_f32 v[84:85], v[84:85], v[246:247] op_sel_hi:[1,0]
	v_pk_mul_f32 v[86:87], v[86:87], v[246:247] op_sel_hi:[1,0]
	ds_read_b64 v[176:177], v241 offset:13888
	ds_read_b64 v[178:179], v241 offset:13904
	s_waitcnt lgkmcnt(6)
	v_mfma_f32_32x32x16_bf16 v[64:79], v[180:183], v[188:191], v[64:79]
	v_pk_mul_f32 v[88:89], v[88:89], v[246:247] op_sel_hi:[1,0]
	v_pk_mul_f32 v[90:91], v[90:91], v[246:247] op_sel_hi:[1,0]
	v_pk_mul_f32 v[92:93], v[92:93], v[246:247] op_sel_hi:[1,0]
	v_pk_mul_f32 v[94:95], v[94:95], v[246:247] op_sel_hi:[1,0]
	ds_read_b64 v[180:181], v241 offset:13920
	ds_read_b64 v[182:183], v241 offset:13936
	s_waitcnt lgkmcnt(6)
	v_mfma_f32_32x32x16_bf16 v[80:95], v[168:171], v[184:187], v[80:95]
	v_pk_mul_f32 v[96:97], v[96:97], v[246:247] op_sel_hi:[1,0]
	v_pk_mul_f32 v[98:99], v[98:99], v[246:247] op_sel_hi:[1,0]
	v_pk_mul_f32 v[100:101], v[100:101], v[246:247] op_sel_hi:[1,0]
	v_pk_mul_f32 v[102:103], v[102:103], v[246:247] op_sel_hi:[1,0]
	s_nop 1
	s_waitcnt lgkmcnt(4)
	v_mfma_f32_32x32x16_bf16 v[80:95], v[172:175], v[188:191], v[80:95]
	v_pk_mul_f32 v[104:105], v[104:105], v[246:247] op_sel_hi:[1,0]
	v_pk_mul_f32 v[106:107], v[106:107], v[246:247] op_sel_hi:[1,0]
	v_pk_mul_f32 v[108:109], v[108:109], v[246:247] op_sel_hi:[1,0]
	v_pk_mul_f32 v[110:111], v[110:111], v[246:247] op_sel_hi:[1,0]
	s_nop 1
	s_waitcnt lgkmcnt(2)
	v_mfma_f32_32x32x16_bf16 v[96:111], v[176:179], v[184:187], v[96:111]
	s_waitcnt lgkmcnt(0)
	v_mfma_f32_32x32x16_bf16 v[96:111], v[180:183], v[188:191], v[96:111]
	s_branch dn1_jn2
dn1_nr2:
	s_nop 1
	s_waitcnt lgkmcnt(6)
	v_mfma_f32_32x32x16_bf16 v[48:63], v[168:171], v[184:187], v[48:63]
	ds_read_b64 v[168:169], v241 offset:9280
	ds_read_b64 v[170:171], v241 offset:9296
	s_waitcnt lgkmcnt(6)
	v_mfma_f32_32x32x16_bf16 v[48:63], v[172:175], v[188:191], v[48:63]
	ds_read_b64 v[172:173], v241 offset:9312
	ds_read_b64 v[174:175], v241 offset:9328
	s_waitcnt lgkmcnt(6)
	v_mfma_f32_32x32x16_bf16 v[64:79], v[176:179], v[184:187], v[64:79]
	ds_read_b64 v[176:177], v241 offset:13888
	ds_read_b64 v[178:179], v241 offset:13904
	s_waitcnt lgkmcnt(6)
	v_mfma_f32_32x32x16_bf16 v[64:79], v[180:183], v[188:191], v[64:79]
	ds_read_b64 v[180:181], v241 offset:13920
	ds_read_b64 v[182:183], v241 offset:13936
	s_waitcnt lgkmcnt(6)
	v_mfma_f32_32x32x16_bf16 v[80:95], v[168:171], v[184:187], v[80:95]
	s_waitcnt lgkmcnt(4)
	v_mfma_f32_32x32x16_bf16 v[80:95], v[172:175], v[188:191], v[80:95]
	s_waitcnt lgkmcnt(2)
	v_mfma_f32_32x32x16_bf16 v[96:111], v[176:179], v[184:187], v[96:111]
	s_waitcnt lgkmcnt(0)
	v_mfma_f32_32x32x16_bf16 v[96:111], v[180:183], v[188:191], v[96:111]
; #define LAS __attribute__((address_space(3)))
; DI unsigned xb_add(unsigned* p, unsigned v) { return __hip_atomic_fetch_add(p, v, __ATOMIC_RELAXED, __HIP_MEMORY_SCOPE_AGENT); }
; DI void st_bf16x4(bf16_t* p, f32x4 v) { u32x2 w; w.x = cvt_pk_bf16(v[0], v[1]); w.y = cvt_pk_bf16(v[2], v[3]); *(u32x2*)p = w; }
; DI int next_item(unsigned* ctr, volatile LAS int* slot) {
;     __syncthreads();
;     if (threadIdx.x == 0) *slot = (int)xb_add(ctr, 1u);
;     __syncthreads();
; template <int DK>
; DI void dense_attn_item(LAS unsigned char* lds, const bf16_t* Qb, int ldq, const bf16_t* Kb, int ldk, const bf16_t* Kpe, const bf16_t* Vt, int nkeys, float sl2, bf16_t* Ob) {
;     ...
; #pragma unroll
;     for (int qg = 0; qg < 2; ++qg) {
;         float l = lsum[qg]; l += __shfl_xor(l, 16); l += __shfl_xor(l, 32);
;         const float inv = 1.f / l;
;         bf16_t* op = Ob + (size_t)(wid * 32 + qg * 16 + r16) * DM + q4 * 4;
; #pragma unroll
;         for (int d = 0; d < 8; ++d) st_bf16x4(op + d * 16, oacc[qg][d] * inv);
;     }
dn1_jn2:
	s_mov_b32 s27, s57
	s_add_u32 s23, s23, 1
	s_cmp_lt_u32 s23, 36
	s_cbranch_scc1 dn1_top
	s_waitcnt vmcnt(0) lgkmcnt(0)
	v_mov_b32_e32 v193, v244
	v_mov_b32_e32 v192, v244
	s_nop 1
	v_permlane32_swap_b32_e32 v193, v192
	v_add_f32_e32 v193, v193, v192
	v_rcp_f32_e32 v192, v193
	s_nop 0
	v_fma_f32 v193, -v193, v192, 1.0
	v_fma_f32 v246, v193, v192, v192
	v_pk_mul_f32 v[48:49], v[48:49], v[246:247] op_sel_hi:[1,0]
	v_pk_mul_f32 v[50:51], v[50:51], v[246:247] op_sel_hi:[1,0]
	v_cvt_pk_bf16_f32 v48, v48, v49
	v_cvt_pk_bf16_f32 v49, v50, v51
	global_store_dwordx2 v250, v[48:49], s[20:21] offset:0
	v_pk_mul_f32 v[52:53], v[52:53], v[246:247] op_sel_hi:[1,0]
	v_pk_mul_f32 v[54:55], v[54:55], v[246:247] op_sel_hi:[1,0]
	v_cvt_pk_bf16_f32 v52, v52, v53
	v_cvt_pk_bf16_f32 v53, v54, v55
	global_store_dwordx2 v250, v[52:53], s[20:21] offset:16
	v_pk_mul_f32 v[56:57], v[56:57], v[246:247] op_sel_hi:[1,0]
	v_pk_mul_f32 v[58:59], v[58:59], v[246:247] op_sel_hi:[1,0]
	v_cvt_pk_bf16_f32 v56, v56, v57
	v_cvt_pk_bf16_f32 v57, v58, v59
	global_store_dwordx2 v250, v[56:57], s[20:21] offset:32
	v_pk_mul_f32 v[60:61], v[60:61], v[246:247] op_sel_hi:[1,0]
	v_pk_mul_f32 v[62:63], v[62:63], v[246:247] op_sel_hi:[1,0]
	v_cvt_pk_bf16_f32 v60, v60, v61
	v_cvt_pk_bf16_f32 v61, v62, v63
	global_store_dwordx2 v250, v[60:61], s[20:21] offset:48
	v_pk_mul_f32 v[64:65], v[64:65], v[246:247] op_sel_hi:[1,0]
	v_pk_mul_f32 v[66:67], v[66:67], v[246:247] op_sel_hi:[1,0]
	v_cvt_pk_bf16_f32 v64, v64, v65
	v_cvt_pk_bf16_f32 v65, v66, v67
	global_store_dwordx2 v250, v[64:65], s[20:21] offset:64
	v_pk_mul_f32 v[68:69], v[68:69], v[246:247] op_sel_hi:[1,0]
	v_pk_mul_f32 v[70:71], v[70:71], v[246:247] op_sel_hi:[1,0]
	v_cvt_pk_bf16_f32 v68, v68, v69
	v_cvt_pk_bf16_f32 v69, v70, v71
	global_store_dwordx2 v250, v[68:69], s[20:21] offset:80
	v_pk_mul_f32 v[72:73], v[72:73], v[246:247] op_sel_hi:[1,0]
	v_pk_mul_f32 v[74:75], v[74:75], v[246:247] op_sel_hi:[1,0]
	v_cvt_pk_bf16_f32 v72, v72, v73
	v_cvt_pk_bf16_f32 v73, v74, v75
	global_store_dwordx2 v250, v[72:73], s[20:21] offset:96
	v_pk_mul_f32 v[76:77], v[76:77], v[246:247] op_sel_hi:[1,0]
	v_pk_mul_f32 v[78:79], v[78:79], v[246:247] op_sel_hi:[1,0]
	v_cvt_pk_bf16_f32 v76, v76, v77
	v_cvt_pk_bf16_f32 v77, v78, v79
	global_store_dwordx2 v250, v[76:77], s[20:21] offset:112
	v_pk_mul_f32 v[80:81], v[80:81], v[246:247] op_sel_hi:[1,0]
	v_pk_mul_f32 v[82:83], v[82:83], v[246:247] op_sel_hi:[1,0]
	v_cvt_pk_bf16_f32 v80, v80, v81
	v_cvt_pk_bf16_f32 v81, v82, v83
	global_store_dwordx2 v250, v[80:81], s[20:21] offset:128
	v_pk_mul_f32 v[84:85], v[84:85], v[246:247] op_sel_hi:[1,0]
	v_pk_mul_f32 v[86:87], v[86:87], v[246:247] op_sel_hi:[1,0]
	v_cvt_pk_bf16_f32 v84, v84, v85
	v_cvt_pk_bf16_f32 v85, v86, v87
	global_store_dwordx2 v250, v[84:85], s[20:21] offset:144
	v_pk_mul_f32 v[88:89], v[88:89], v[246:247] op_sel_hi:[1,0]
	v_pk_mul_f32 v[90:91], v[90:91], v[246:247] op_sel_hi:[1,0]
	v_cvt_pk_bf16_f32 v88, v88, v89
	v_cvt_pk_bf16_f32 v89, v90, v91
	global_store_dwordx2 v250, v[88:89], s[20:21] offset:160
	v_pk_mul_f32 v[92:93], v[92:93], v[246:247] op_sel_hi:[1,0]
	v_pk_mul_f32 v[94:95], v[94:95], v[246:247] op_sel_hi:[1,0]
	v_cvt_pk_bf16_f32 v92, v92, v93
	v_cvt_pk_bf16_f32 v93, v94, v95
	global_store_dwordx2 v250, v[92:93], s[20:21] offset:176
	v_pk_mul_f32 v[96:97], v[96:97], v[246:247] op_sel_hi:[1,0]
	v_pk_mul_f32 v[98:99], v[98:99], v[246:247] op_sel_hi:[1,0]
	v_cvt_pk_bf16_f32 v96, v96, v97
	v_cvt_pk_bf16_f32 v97, v98, v99
	global_store_dwordx2 v250, v[96:97], s[20:21] offset:192
	v_pk_mul_f32 v[100:101], v[100:101], v[246:247] op_sel_hi:[1,0]
	v_pk_mul_f32 v[102:103], v[102:103], v[246:247] op_sel_hi:[1,0]
	v_cvt_pk_bf16_f32 v100, v100, v101
	v_cvt_pk_bf16_f32 v101, v102, v103
	global_store_dwordx2 v250, v[100:101], s[20:21] offset:208
	v_pk_mul_f32 v[104:105], v[104:105], v[246:247] op_sel_hi:[1,0]
	v_pk_mul_f32 v[106:107], v[106:107], v[246:247] op_sel_hi:[1,0]
	v_cvt_pk_bf16_f32 v104, v104, v105
	v_cvt_pk_bf16_f32 v105, v106, v107
	global_store_dwordx2 v250, v[104:105], s[20:21] offset:224
	v_pk_mul_f32 v[108:109], v[108:109], v[246:247] op_sel_hi:[1,0]
	v_pk_mul_f32 v[110:111], v[110:111], v[246:247] op_sel_hi:[1,0]
	v_cvt_pk_bf16_f32 v108, v108, v109
	v_cvt_pk_bf16_f32 v109, v110, v111
	global_store_dwordx2 v250, v[108:109], s[20:21] offset:240
	v_mov_b32_e32 v133, 0
	s_waitcnt vmcnt(0)
	s_barrier
	s_and_saveexec_b64 s[0:1], s[24:25]
	s_cbranch_execz .LBB0_2592
	s_mov_b64 s[4:5], exec
	v_mbcnt_lo_u32_b32 v0, s4, 0
	v_mbcnt_hi_u32_b32 v0, s5, v0
	v_cmp_eq_u32_e32 vcc, 0, v0
	s_and_saveexec_b64 s[2:3], vcc
	s_cbranch_execz .LBB0_2591
	s_bcnt1_i32_b64 s4, s[4:5]
	v_mov_b32_e32 v1, s4
	global_atomic_add v1, v133, v1, s[34:35] sc0
	s_branch .LBB0_2591
